# dilated-combine: all 4 iterations' loads hoisted and issued together (1 round trip instead of 8)
# baseline (speedup 1.0000x reference)
; #define MFMA(a, b, c) __builtin_amdgcn_mfma_f32_32x32x16_bf16((a), (b), (c), 0, 0, 0)
; DI float bf2f(u16 v) { return __uint_as_float((unsigned)v << 16); }
; DI u16 f2bf(float x) { return (u16)(pk2(x, 0.f) & 0xffffu); }
; DI float lo16(unsigned w) { return __uint_as_float(w << 16); }
; DI float hi16(unsigned w) { return __uint_as_float(w & 0xffff0000u); }
; DI float siluf_(float x) { return x / (1.f + __expf(-x)); }
; DI void pool_item(const Params& p, int l, int it, char* lds) {
;     ...
;     const int ch = tid, w = 2 << g;
;     float s = 0.f;
;     for (int r = 17 - w; r <= 16; ++r) s += bf2f(cin[r * 256 + ch]);
; #pragma unroll 4
;     for (int i = 0; i < 32; ++i) {
;       const int t = q0 + i; const int cnt = (t + 1 < w) ? t + 1 : w;
;       const float self = bf2f(cin[(i + 16) * 256 + ch]);
;       *(u16*)(pl + i * 528 + ch * 2) = f2bf(s / (float)cnt - self);
;       s += bf2f(cin[(i + 17) * 256 + ch]) - bf2f(cin[(i + 17 - w) * 256 + ch]);
;     }
;   }
;   __syncthreads();
;   f32x16 acc[2];
; #pragma unroll
;   for (int r = 0; r < 16; ++r) { acc[0][r] = 0.f; acc[1][r] = 0.f; }
; #pragma unroll
;   for (int s4 = 0; s4 < 4; ++s4) {
;     const bf16x8 bf = *(const bf16x8*)(pl + l31 * 528 + (g * 64 + 16 * s4 + 8 * hi) * 2);
; #pragma unroll
;     for (int dt = 0; dt < 2; ++dt) acc[dt] = MFMA(af[s4 * 2 + dt], bf, acc[dt]);
;   }
;   u16* y = (u16*)(ws_ + OFF_XB);
; #pragma unroll
;   for (int dt = 0; dt < 2; ++dt)
; #pragma unroll
;     for (int g4 = 0; g4 < 4; ++g4) {
;       const int col = g * 64 + dt * 32 + 8 * g4 + 4 * hi;
;       const f32x4 ps = psv[dt * 4 + g4];
;       const u32x2 z = zv[dt * 4 + g4];
;       u32x2 v;
;       v[0] = pk2(acc[dt][4 * g4] * ps[0] * siluf_(lo16(z[0])), acc[dt][4 * g4 + 1] * ps[1] * siluf_(hi16(z[0])));
;       v[1] = pk2(acc[dt][4 * g4 + 2] * ps[2] * siluf_(lo16(z[1])), acc[dt][4 * g4 + 3] * ps[3] * siluf_(hi16(z[1])));
;       *(u32x2*)(y + tok * 1024 + 512 + col) = v;
;     }
.LBB0_464:
	v_add_u32_e32 v15, s2, v118
	v_add_u32_e32 v16, 1, v15
	v_min_i32_e32 v16, v16, v9
	v_cvt_f32_i32_e32 v16, v16
	s_waitcnt lgkmcnt(0)
	v_lshlrev_b32_e32 v14, 16, v14
	s_add_i32 s2, s2, 4
	s_cmp_lg_u32 s2, 32
	v_div_scale_f32 v17, s[4:5], v16, v16, v12
	v_rcp_f32_e32 v18, v17
	s_nop 0
	v_fma_f32 v19, -v17, v18, 1.0
	v_fmac_f32_e32 v18, v19, v18
	v_div_scale_f32 v19, vcc, v12, v16, v12
	v_mul_f32_e32 v20, v19, v18
	v_fma_f32 v21, -v17, v20, v19
	v_fmac_f32_e32 v20, v21, v18
	v_fma_f32 v17, -v17, v20, v19
	v_div_fmas_f32 v17, v17, v18, v20
	v_div_fixup_f32 v16, v17, v16, v12
	v_sub_f32_e32 v14, v16, v14
	v_cvt_pk_bf16_f32 v14, v14, s0
	ds_write_b16 v11, v14
	v_add_u32_e32 v16, v13, v10
	ds_read_u16 v14, v16 offset:512
	ds_read_u16 v17, v13 offset:512
	s_waitcnt lgkmcnt(1)
	v_lshlrev_b32_e32 v14, 16, v14
	s_waitcnt lgkmcnt(0)
	v_lshlrev_b32_e32 v17, 16, v17
	v_sub_f32_e32 v14, v17, v14
	v_add_f32_e32 v12, v12, v14
	v_add_u32_e32 v14, 2, v15
	v_min_i32_e32 v14, v14, v9
	v_cvt_f32_i32_e32 v14, v14
	v_div_scale_f32 v18, s[4:5], v14, v14, v12
	v_rcp_f32_e32 v19, v18
	s_nop 0
	v_fma_f32 v20, -v18, v19, 1.0
	v_fmac_f32_e32 v19, v20, v19
	v_div_scale_f32 v20, vcc, v12, v14, v12
	v_mul_f32_e32 v21, v20, v19
	v_fma_f32 v22, -v18, v21, v20
	v_fmac_f32_e32 v21, v22, v19
	v_fma_f32 v18, -v18, v21, v20
	v_div_fmas_f32 v18, v18, v19, v21
	v_div_fixup_f32 v14, v18, v14, v12
	v_sub_f32_e32 v14, v14, v17
	v_cvt_pk_bf16_f32 v14, v14, s0
	ds_write_b16 v11, v14 offset:528
	ds_read_u16 v14, v16 offset:1024
	ds_read_u16 v17, v13 offset:1024
	s_waitcnt lgkmcnt(1)
	v_lshlrev_b32_e32 v14, 16, v14
	s_waitcnt lgkmcnt(0)
	v_lshlrev_b32_e32 v17, 16, v17
	v_sub_f32_e32 v14, v17, v14
	v_add_f32_e32 v12, v12, v14
	v_add_u32_e32 v14, 3, v15
	v_min_i32_e32 v14, v14, v9
	v_cvt_f32_i32_e32 v14, v14
	v_div_scale_f32 v18, s[4:5], v14, v14, v12
	v_rcp_f32_e32 v19, v18
	s_nop 0
	v_fma_f32 v20, -v18, v19, 1.0
	v_fmac_f32_e32 v19, v20, v19
	v_div_scale_f32 v20, vcc, v12, v14, v12
	v_mul_f32_e32 v21, v20, v19
	v_fma_f32 v22, -v18, v21, v20
	v_fmac_f32_e32 v21, v22, v19
	v_fma_f32 v18, -v18, v21, v20
	v_div_fmas_f32 v18, v18, v19, v21
	v_div_fixup_f32 v14, v18, v14, v12
	v_sub_f32_e32 v14, v14, v17
	v_cvt_pk_bf16_f32 v14, v14, s0
	ds_write_b16 v11, v14 offset:1056
	ds_read_u16 v14, v16 offset:1536
	ds_read_u16 v17, v13 offset:1536
	s_waitcnt lgkmcnt(1)
	v_lshlrev_b32_e32 v14, 16, v14
	s_waitcnt lgkmcnt(0)
	v_lshlrev_b32_e32 v17, 16, v17
	v_sub_f32_e32 v14, v17, v14
	v_add_f32_e32 v12, v12, v14
	v_add_u32_e32 v14, 4, v15
	v_min_i32_e32 v14, v14, v9
	v_cvt_f32_i32_e32 v14, v14
	v_div_scale_f32 v15, s[4:5], v14, v14, v12
	v_rcp_f32_e32 v18, v15
	s_nop 0
	v_fma_f32 v19, -v15, v18, 1.0
	v_fmac_f32_e32 v18, v19, v18
	v_div_scale_f32 v19, vcc, v12, v14, v12
	v_mul_f32_e32 v20, v19, v18
	v_fma_f32 v21, -v15, v20, v19
	v_fmac_f32_e32 v20, v21, v18
	v_fma_f32 v15, -v15, v20, v19
	v_div_fmas_f32 v15, v15, v18, v20
	v_div_fixup_f32 v14, v15, v14, v12
	v_sub_f32_e32 v14, v14, v17
	v_cvt_pk_bf16_f32 v14, v14, s0
	ds_write_b16 v11, v14 offset:1584
	v_add_u32_e32 v15, 0x800, v13
	ds_read_u16 v14, v13 offset:2048
	ds_read_u16 v13, v16 offset:2048
	v_add_u32_e32 v11, 0x840, v11
	s_waitcnt lgkmcnt(1)
	v_lshlrev_b32_e32 v16, 16, v14
	s_waitcnt lgkmcnt(0)
	v_lshlrev_b32_e32 v13, 16, v13
	v_sub_f32_e32 v13, v16, v13
	v_add_f32_e32 v12, v12, v13
	v_mov_b32_e32 v13, v15
	s_cbranch_scc1 .LBB0_464
	v_mul_u32_u24_e32 v9, 0x210, v120
	v_and_b32_e32 v8, 0xffffff80, v8
	v_add3_u32 v124, v9, v178, v8
	s_barrier
	ds_read_b128 v[8:11], v124 offset:24576
	ds_read_b128 v[120:123], v124 offset:24608
	s_waitcnt vmcnt(23) lgkmcnt(1)
	v_mfma_f32_32x32x16_bf16 v[16:31], v[0:3], v[8:11], 0
	v_mov_b32_e32 v183, v179
	s_mov_b64 s[2:3], 0xd390000
	v_mov_b32_e32 v185, v179
	s_mov_b64 s[4:5], 0x8000
	v_add_u32_e32 v118, 32, v118
	s_waitcnt vmcnt(22)
	v_mfma_f32_32x32x16_bf16 v[0:15], v[4:7], v[8:11], 0
	s_waitcnt vmcnt(21) lgkmcnt(0)
	v_mfma_f32_32x32x16_bf16 v[16:31], v[76:79], v[120:123], v[16:31]
	ds_read_b128 v[76:79], v124 offset:24640
	s_waitcnt vmcnt(19)
	v_mfma_f32_32x32x16_bf16 v[0:15], v[84:87], v[120:123], v[0:15]
	s_waitcnt lgkmcnt(0)
	v_mfma_f32_32x32x16_bf16 v[16:31], v[64:67], v[76:79], v[16:31]
	ds_read_b128 v[64:67], v124 offset:24672
	s_waitcnt vmcnt(18)
	v_mfma_f32_32x32x16_bf16 v[0:15], v[80:83], v[76:79], v[0:15]
	s_waitcnt vmcnt(17) lgkmcnt(0)
	v_mfma_f32_32x32x16_bf16 v[16:31], v[68:71], v[64:67], v[16:31]
	s_waitcnt vmcnt(11)
	v_lshlrev_b32_e32 v68, 16, v112
	v_and_b32_e32 v69, 0xffff0000, v112
	v_mfma_f32_32x32x16_bf16 v[0:15], v[72:75], v[64:67], v[0:15]
	v_mul_f32_e32 v66, 0xbfb8aa3b, v68
	s_nop 6
	v_mul_f32_e64 v16, v60, v16
	v_mul_f32_e64 v17, v61, v17
	v_mul_f32_e32 v60, 0xbfb8aa3b, v69
	v_exp_f32_e32 v66, v66
	v_exp_f32_e32 v67, v60
	v_lshlrev_b64 v[64:65], 11, v[114:115]
	v_lshl_add_u64 v[64:65], s[0:1], 0, v[64:65]
	s_mov_b64 s[0:1], 0x2a40400
	v_pk_add_f32 v[60:61], v[66:67], 1.0 op_sel_hi:[1,0]
	v_lshl_add_u64 v[64:65], v[64:65], 0, s[0:1]
	v_div_scale_f32 v66, s[0:1], v61, v61, v69
	v_rcp_f32_e32 v67, v66
	v_pk_mul_f32 v[18:19], v[62:63], v[18:19]
	v_pk_mul_f32 v[20:21], v[56:57], v[20:21]
	v_pk_mul_f32 v[22:23], v[58:59], v[22:23]
	v_fma_f32 v70, -v66, v67, 1.0
	v_fmac_f32_e32 v67, v70, v67
	v_div_scale_f32 v70, vcc, v69, v61, v69
	v_mul_f32_e32 v71, v70, v67
	v_fma_f32 v72, -v66, v71, v70
	v_fmac_f32_e32 v71, v72, v67
	v_fma_f32 v66, -v66, v71, v70
	v_div_fmas_f32 v66, v66, v67, v71
	v_div_fixup_f32 v61, v66, v61, v69
	v_div_scale_f32 v66, s[0:1], v60, v60, v68
	v_rcp_f32_e32 v67, v66
	s_waitcnt vmcnt(7)
; DI float lo16(unsigned w) { return __uint_as_float(w << 16); }
; DI float hi16(unsigned w) { return __uint_as_float(w & 0xffff0000u); }
; DI float siluf_(float x) { return x / (1.f + __expf(-x)); }
; DI void pool_item(const Params& p, int l, int it, char* lds) {
;     ...
;   u16* y = (u16*)(ws_ + OFF_XB);
; #pragma unroll
;   for (int dt = 0; dt < 2; ++dt)
; #pragma unroll
;     for (int g4 = 0; g4 < 4; ++g4) {
;       const int col = g * 64 + dt * 32 + 8 * g4 + 4 * hi;
;       const f32x4 ps = psv[dt * 4 + g4];
;       const u32x2 z = zv[dt * 4 + g4];
;       u32x2 v;
;       v[0] = pk2(acc[dt][4 * g4] * ps[0] * siluf_(lo16(z[0])), acc[dt][4 * g4 + 1] * ps[1] * siluf_(hi16(z[0])));
;       v[1] = pk2(acc[dt][4 * g4 + 2] * ps[2] * siluf_(lo16(z[1])), acc[dt][4 * g4 + 3] * ps[3] * siluf_(hi16(z[1])));
;       *(u32x2*)(y + tok * 1024 + 512 + col) = v;
;     }
	v_pk_mul_f32 v[0:1], v[44:45], v[0:1]
	v_pk_mul_f32 v[2:3], v[46:47], v[2:3]
	v_fma_f32 v69, -v66, v67, 1.0
	v_fmac_f32_e32 v67, v69, v67
	v_div_scale_f32 v69, vcc, v68, v60, v68
	v_mul_f32_e32 v70, v69, v67
	v_fma_f32 v71, -v66, v70, v69
	v_fmac_f32_e32 v70, v71, v67
	v_fma_f32 v66, -v66, v70, v69
	v_div_fmas_f32 v66, v66, v67, v70
	v_div_fixup_f32 v60, v66, v60, v68
	v_pk_mul_f32 v[16:17], v[60:61], v[16:17]
	v_lshlrev_b32_e32 v61, 16, v113
	v_and_b32_e32 v66, 0xffff0000, v113
	v_cvt_pk_bf16_f32 v60, v16, v17
	v_mul_f32_e32 v16, 0xbfb8aa3b, v61
	v_mul_f32_e32 v17, 0xbfb8aa3b, v66
	v_exp_f32_e32 v16, v16
	v_exp_f32_e32 v17, v17
	s_nop 0
	v_pk_add_f32 v[16:17], v[16:17], 1.0 op_sel_hi:[1,0]
	s_nop 0
	v_div_scale_f32 v62, s[0:1], v17, v17, v66
	v_rcp_f32_e32 v63, v62
	s_nop 0
	v_fma_f32 v67, -v62, v63, 1.0
	v_fmac_f32_e32 v63, v67, v63
	v_div_scale_f32 v67, vcc, v66, v17, v66
	v_mul_f32_e32 v68, v67, v63
	v_fma_f32 v69, -v62, v68, v67
	v_fmac_f32_e32 v68, v69, v63
	v_fma_f32 v62, -v62, v68, v67
	v_div_fmas_f32 v62, v62, v63, v68
	v_div_fixup_f32 v17, v62, v17, v66
	v_div_scale_f32 v62, s[0:1], v16, v16, v61
	v_rcp_f32_e32 v63, v62
	s_nop 0
	v_fma_f32 v66, -v62, v63, 1.0
	v_fmac_f32_e32 v63, v66, v63
	v_div_scale_f32 v66, vcc, v61, v16, v61
	v_mul_f32_e32 v67, v66, v63
	v_fma_f32 v68, -v62, v67, v66
	v_fmac_f32_e32 v67, v68, v63
	v_fma_f32 v62, -v62, v67, v66
	v_div_fmas_f32 v62, v62, v63, v67
	v_div_fixup_f32 v16, v62, v16, v61
	v_pk_mul_f32 v[16:17], v[16:17], v[18:19]
	s_nop 0
	v_cvt_pk_bf16_f32 v61, v16, v17
	v_lshl_add_u64 v[16:17], v[110:111], 1, v[64:65]
	global_store_dwordx2 v[16:17], v[60:61], off
	v_lshlrev_b32_e32 v60, 16, v108
	v_and_b32_e32 v61, 0xffff0000, v108
	v_mul_f32_e32 v18, 0xbfb8aa3b, v60
	v_mul_f32_e32 v19, 0xbfb8aa3b, v61
	v_exp_f32_e32 v18, v18
	v_exp_f32_e32 v19, v19
	s_nop 0
	v_pk_add_f32 v[18:19], v[18:19], 1.0 op_sel_hi:[1,0]
	s_nop 0
	v_div_scale_f32 v56, s[0:1], v19, v19, v61
	v_rcp_f32_e32 v57, v56
	s_nop 0
	v_fma_f32 v62, -v56, v57, 1.0
	v_fmac_f32_e32 v57, v62, v57
	v_div_scale_f32 v62, vcc, v61, v19, v61
	v_mul_f32_e32 v63, v62, v57
	v_fma_f32 v66, -v56, v63, v62
	v_fmac_f32_e32 v63, v66, v57
	v_fma_f32 v56, -v56, v63, v62
	v_div_fmas_f32 v56, v56, v57, v63
	v_div_fixup_f32 v19, v56, v19, v61
	v_div_scale_f32 v56, s[0:1], v18, v18, v60
	v_rcp_f32_e32 v57, v56
	s_nop 0
	v_fma_f32 v61, -v56, v57, 1.0
	v_fmac_f32_e32 v57, v61, v57
	v_div_scale_f32 v61, vcc, v60, v18, v60
	v_mul_f32_e32 v62, v61, v57
	v_fma_f32 v63, -v56, v62, v61
	v_fmac_f32_e32 v62, v63, v57
	v_fma_f32 v56, -v56, v62, v61
	v_div_fmas_f32 v56, v56, v57, v62
	v_div_fixup_f32 v18, v56, v18, v60
	v_pk_mul_f32 v[18:19], v[18:19], v[20:21]
	v_and_b32_e32 v56, 0xffff0000, v109
	v_cvt_pk_bf16_f32 v18, v18, v19
	v_lshlrev_b32_e32 v19, 16, v109
	v_mul_f32_e32 v20, 0xbfb8aa3b, v19
	v_mul_f32_e32 v21, 0xbfb8aa3b, v56
	v_exp_f32_e32 v20, v20
	v_exp_f32_e32 v21, v21
	s_nop 0
	v_pk_add_f32 v[20:21], v[20:21], 1.0 op_sel_hi:[1,0]
	s_nop 0
	v_div_scale_f32 v57, s[0:1], v21, v21, v56
	v_rcp_f32_e32 v58, v57
	s_nop 0
	v_fma_f32 v59, -v57, v58, 1.0
	v_fmac_f32_e32 v58, v59, v58
	v_div_scale_f32 v59, vcc, v56, v21, v56
	v_mul_f32_e32 v60, v59, v58
	v_fma_f32 v61, -v57, v60, v59
	v_fmac_f32_e32 v60, v61, v58
	v_fma_f32 v57, -v57, v60, v59
	v_div_fmas_f32 v57, v57, v58, v60
	v_div_fixup_f32 v21, v57, v21, v56
	v_div_scale_f32 v56, s[0:1], v20, v20, v19
	v_rcp_f32_e32 v57, v56
	s_nop 0
	v_fma_f32 v58, -v56, v57, 1.0
	v_fmac_f32_e32 v57, v58, v57
	v_div_scale_f32 v58, vcc, v19, v20, v19
	v_mul_f32_e32 v59, v58, v57
	v_fma_f32 v60, -v56, v59, v58
	v_fmac_f32_e32 v59, v60, v57
	v_fma_f32 v56, -v56, v59, v58
	v_div_fmas_f32 v56, v56, v57, v59
	v_div_fixup_f32 v20, v56, v20, v19
	v_pk_mul_f32 v[20:21], v[20:21], v[22:23]
	v_lshlrev_b32_e32 v22, 16, v104
	v_cvt_pk_bf16_f32 v19, v20, v21
	v_lshl_add_u64 v[20:21], v[106:107], 1, v[64:65]
	v_and_b32_e32 v23, 0xffff0000, v104
	global_store_dwordx2 v[20:21], v[18:19], off
	v_mul_f32_e32 v18, 0xbfb8aa3b, v22
	v_mul_f32_e32 v19, 0xbfb8aa3b, v23
	v_exp_f32_e32 v18, v18
	v_exp_f32_e32 v19, v19
	v_pk_mul_f32 v[20:21], v[52:53], v[24:25]
	v_pk_add_f32 v[18:19], v[18:19], 1.0 op_sel_hi:[1,0]
	s_nop 0
	v_div_scale_f32 v24, s[0:1], v19, v19, v23
	v_rcp_f32_e32 v25, v24
	s_nop 0
	v_fma_f32 v52, -v24, v25, 1.0
	v_fmac_f32_e32 v25, v52, v25
	v_div_scale_f32 v52, vcc, v23, v19, v23
	v_mul_f32_e32 v53, v52, v25
	v_fma_f32 v56, -v24, v53, v52
	v_fmac_f32_e32 v53, v56, v25
	v_fma_f32 v24, -v24, v53, v52
	v_div_fmas_f32 v24, v24, v25, v53
	v_div_fixup_f32 v19, v24, v19, v23
	v_div_scale_f32 v23, s[0:1], v18, v18, v22
	v_rcp_f32_e32 v24, v23
	s_nop 0
	v_fma_f32 v25, -v23, v24, 1.0
	v_fmac_f32_e32 v24, v25, v24
	v_div_scale_f32 v25, vcc, v22, v18, v22
	v_mul_f32_e32 v52, v25, v24
	v_fma_f32 v53, -v23, v52, v25
	v_fmac_f32_e32 v52, v53, v24
	v_fma_f32 v23, -v23, v52, v25
	v_div_fmas_f32 v23, v23, v24, v52
	v_div_fixup_f32 v18, v23, v18, v22
	v_pk_mul_f32 v[18:19], v[18:19], v[20:21]
	v_and_b32_e32 v24, 0xffff0000, v105
	v_cvt_pk_bf16_f32 v18, v18, v19
	v_lshlrev_b32_e32 v19, 16, v105
	v_mul_f32_e32 v20, 0xbfb8aa3b, v19
	v_mul_f32_e32 v21, 0xbfb8aa3b, v24
	v_exp_f32_e32 v20, v20
	v_exp_f32_e32 v21, v21
	v_pk_mul_f32 v[22:23], v[54:55], v[26:27]
	v_pk_add_f32 v[20:21], v[20:21], 1.0 op_sel_hi:[1,0]
	s_nop 0
	v_div_scale_f32 v25, s[0:1], v21, v21, v24
	v_rcp_f32_e32 v26, v25
	s_nop 0
	v_fma_f32 v27, -v25, v26, 1.0
	v_fmac_f32_e32 v26, v27, v26
	v_div_scale_f32 v27, vcc, v24, v21, v24
	v_mul_f32_e32 v52, v27, v26
	v_fma_f32 v53, -v25, v52, v27
	v_fmac_f32_e32 v52, v53, v26
	v_fma_f32 v25, -v25, v52, v27
	v_div_fmas_f32 v25, v25, v26, v52
; DI float lo16(unsigned w) { return __uint_as_float(w << 16); }
; DI float hi16(unsigned w) { return __uint_as_float(w & 0xffff0000u); }
; DI float siluf_(float x) { return x / (1.f + __expf(-x)); }
; DI void pool_item(const Params& p, int l, int it, char* lds) {
;     ...
;   u16* y = (u16*)(ws_ + OFF_XB);
; #pragma unroll
;   for (int dt = 0; dt < 2; ++dt)
; #pragma unroll
;     for (int g4 = 0; g4 < 4; ++g4) {
;       const int col = g * 64 + dt * 32 + 8 * g4 + 4 * hi;
;       const f32x4 ps = psv[dt * 4 + g4];
;       const u32x2 z = zv[dt * 4 + g4];
;       u32x2 v;
;       v[0] = pk2(acc[dt][4 * g4] * ps[0] * siluf_(lo16(z[0])), acc[dt][4 * g4 + 1] * ps[1] * siluf_(hi16(z[0])));
;       v[1] = pk2(acc[dt][4 * g4 + 2] * ps[2] * siluf_(lo16(z[1])), acc[dt][4 * g4 + 3] * ps[3] * siluf_(hi16(z[1])));
;       *(u32x2*)(y + tok * 1024 + 512 + col) = v;
;     }
	v_div_fixup_f32 v21, v25, v21, v24
	v_div_scale_f32 v24, s[0:1], v20, v20, v19
	v_rcp_f32_e32 v25, v24
	s_nop 0
	v_fma_f32 v26, -v24, v25, 1.0
	v_fmac_f32_e32 v25, v26, v25
	v_div_scale_f32 v26, vcc, v19, v20, v19
	v_mul_f32_e32 v27, v26, v25
	v_fma_f32 v52, -v24, v27, v26
	v_fmac_f32_e32 v27, v52, v25
	v_fma_f32 v24, -v24, v27, v26
	v_div_fmas_f32 v24, v24, v25, v27
	v_div_fixup_f32 v20, v24, v20, v19
	v_pk_mul_f32 v[20:21], v[20:21], v[22:23]
	v_lshlrev_b32_e32 v22, 16, v100
	v_cvt_pk_bf16_f32 v19, v20, v21
	v_lshl_add_u64 v[20:21], v[102:103], 1, v[64:65]
	v_and_b32_e32 v23, 0xffff0000, v100
	global_store_dwordx2 v[20:21], v[18:19], off
	v_mul_f32_e32 v18, 0xbfb8aa3b, v22
	v_mul_f32_e32 v19, 0xbfb8aa3b, v23
	v_exp_f32_e32 v18, v18
	v_exp_f32_e32 v19, v19
	v_pk_mul_f32 v[20:21], v[48:49], v[28:29]
	v_pk_add_f32 v[18:19], v[18:19], 1.0 op_sel_hi:[1,0]
	s_nop 0
	v_div_scale_f32 v24, s[0:1], v19, v19, v23
	v_rcp_f32_e32 v25, v24
	s_nop 0
	v_fma_f32 v26, -v24, v25, 1.0
	v_fmac_f32_e32 v25, v26, v25
	v_div_scale_f32 v26, vcc, v23, v19, v23
	v_mul_f32_e32 v27, v26, v25
	v_fma_f32 v28, -v24, v27, v26
	v_fmac_f32_e32 v27, v28, v25
	v_fma_f32 v24, -v24, v27, v26
	v_div_fmas_f32 v24, v24, v25, v27
	v_div_fixup_f32 v19, v24, v19, v23
	v_div_scale_f32 v23, s[0:1], v18, v18, v22
	v_rcp_f32_e32 v24, v23
	s_nop 0
	v_fma_f32 v25, -v23, v24, 1.0
	v_fmac_f32_e32 v24, v25, v24
	v_div_scale_f32 v25, vcc, v22, v18, v22
	v_mul_f32_e32 v26, v25, v24
	v_fma_f32 v27, -v23, v26, v25
	v_fmac_f32_e32 v26, v27, v24
	v_fma_f32 v23, -v23, v26, v25
	v_div_fmas_f32 v23, v23, v24, v26
	v_div_fixup_f32 v18, v23, v18, v22
	v_pk_mul_f32 v[18:19], v[18:19], v[20:21]
	v_and_b32_e32 v24, 0xffff0000, v101
	v_cvt_pk_bf16_f32 v18, v18, v19
	v_lshlrev_b32_e32 v19, 16, v101
	v_mul_f32_e32 v20, 0xbfb8aa3b, v19
	v_mul_f32_e32 v21, 0xbfb8aa3b, v24
	v_exp_f32_e32 v20, v20
	v_exp_f32_e32 v21, v21
	v_pk_mul_f32 v[22:23], v[50:51], v[30:31]
	v_pk_add_f32 v[20:21], v[20:21], 1.0 op_sel_hi:[1,0]
	s_nop 0
	v_div_scale_f32 v25, s[0:1], v21, v21, v24
	v_rcp_f32_e32 v26, v25
	s_nop 0
	v_fma_f32 v27, -v25, v26, 1.0
	v_fmac_f32_e32 v26, v27, v26
	v_div_scale_f32 v27, vcc, v24, v21, v24
	v_mul_f32_e32 v28, v27, v26
	v_fma_f32 v29, -v25, v28, v27
	v_fmac_f32_e32 v28, v29, v26
	v_fma_f32 v25, -v25, v28, v27
	v_div_fmas_f32 v25, v25, v26, v28
	v_div_fixup_f32 v21, v25, v21, v24
	v_div_scale_f32 v24, s[0:1], v20, v20, v19
	v_rcp_f32_e32 v25, v24
	s_nop 0
	v_fma_f32 v26, -v24, v25, 1.0
	v_fmac_f32_e32 v25, v26, v25
	v_div_scale_f32 v26, vcc, v19, v20, v19
	v_mul_f32_e32 v27, v26, v25
	v_fma_f32 v28, -v24, v27, v26
	v_fmac_f32_e32 v27, v28, v25
	v_fma_f32 v24, -v24, v27, v26
	v_div_fmas_f32 v24, v24, v25, v27
	v_div_fixup_f32 v20, v24, v20, v19
	v_pk_mul_f32 v[20:21], v[20:21], v[22:23]
	s_nop 0
	v_cvt_pk_bf16_f32 v19, v20, v21
	v_lshl_add_u64 v[20:21], v[98:99], 1, v[64:65]
	global_store_dwordx2 v[20:21], v[18:19], off
	s_waitcnt vmcnt(7)
	v_lshlrev_b32_e32 v20, 16, v96
	v_and_b32_e32 v21, 0xffff0000, v96
	v_mul_f32_e32 v18, 0xbfb8aa3b, v20
	v_mul_f32_e32 v19, 0xbfb8aa3b, v21
	v_exp_f32_e32 v18, v18
	v_exp_f32_e32 v19, v19
	s_nop 0
	v_pk_add_f32 v[18:19], v[18:19], 1.0 op_sel_hi:[1,0]
	s_nop 0
	v_div_scale_f32 v22, s[0:1], v19, v19, v21
	v_rcp_f32_e32 v23, v22
	s_nop 0
	v_fma_f32 v24, -v22, v23, 1.0
	v_fmac_f32_e32 v23, v24, v23
	v_div_scale_f32 v24, vcc, v21, v19, v21
	v_mul_f32_e32 v25, v24, v23
	v_fma_f32 v26, -v22, v25, v24
	v_fmac_f32_e32 v25, v26, v23
	v_fma_f32 v22, -v22, v25, v24
	v_div_fmas_f32 v22, v22, v23, v25
	v_div_fixup_f32 v19, v22, v19, v21
	v_div_scale_f32 v21, s[0:1], v18, v18, v20
	v_rcp_f32_e32 v22, v21
	s_nop 0
	v_fma_f32 v23, -v21, v22, 1.0
	v_fmac_f32_e32 v22, v23, v22
	v_div_scale_f32 v23, vcc, v20, v18, v20
	v_mul_f32_e32 v24, v23, v22
	v_fma_f32 v25, -v21, v24, v23
	v_fmac_f32_e32 v24, v25, v22
	v_fma_f32 v21, -v21, v24, v23
	v_div_fmas_f32 v21, v21, v22, v24
	v_div_fixup_f32 v18, v21, v18, v20
	v_pk_mul_f32 v[0:1], v[18:19], v[0:1]
	v_and_b32_e32 v20, 0xffff0000, v97
	v_cvt_pk_bf16_f32 v0, v0, v1
	v_lshlrev_b32_e32 v1, 16, v97
	v_mul_f32_e32 v18, 0xbfb8aa3b, v1
	v_mul_f32_e32 v19, 0xbfb8aa3b, v20
	v_exp_f32_e32 v18, v18
	v_exp_f32_e32 v19, v19
	s_nop 0
	v_pk_add_f32 v[18:19], v[18:19], 1.0 op_sel_hi:[1,0]
	s_nop 0
	v_div_scale_f32 v21, s[0:1], v19, v19, v20
	v_rcp_f32_e32 v22, v21
	s_nop 0
	v_fma_f32 v23, -v21, v22, 1.0
	v_fmac_f32_e32 v22, v23, v22
	v_div_scale_f32 v23, vcc, v20, v19, v20
	v_mul_f32_e32 v24, v23, v22
	v_fma_f32 v25, -v21, v24, v23
	v_fmac_f32_e32 v24, v25, v22
	v_fma_f32 v21, -v21, v24, v23
	v_div_fmas_f32 v21, v21, v22, v24
	v_div_fixup_f32 v19, v21, v19, v20
	v_div_scale_f32 v20, s[0:1], v18, v18, v1
	v_rcp_f32_e32 v21, v20
	s_nop 0
	v_fma_f32 v22, -v20, v21, 1.0
	v_fmac_f32_e32 v21, v22, v21
	v_div_scale_f32 v22, vcc, v1, v18, v1
	v_mul_f32_e32 v23, v22, v21
	v_fma_f32 v24, -v20, v23, v22
	v_fmac_f32_e32 v23, v24, v21
	v_fma_f32 v20, -v20, v23, v22
	v_div_fmas_f32 v20, v20, v21, v23
	v_div_fixup_f32 v18, v20, v18, v1
	v_pk_mul_f32 v[2:3], v[18:19], v[2:3]
	s_waitcnt vmcnt(6)
; DI float lo16(unsigned w) { return __uint_as_float(w << 16); }
; DI float hi16(unsigned w) { return __uint_as_float(w & 0xffff0000u); }
; DI float siluf_(float x) { return x / (1.f + __expf(-x)); }
; DI void pool_item(const Params& p, int l, int it, char* lds) {
;     ...
;   u16* y = (u16*)(ws_ + OFF_XB);
; #pragma unroll
;   for (int dt = 0; dt < 2; ++dt)
; #pragma unroll
;     for (int g4 = 0; g4 < 4; ++g4) {
;       const int col = g * 64 + dt * 32 + 8 * g4 + 4 * hi;
;       const f32x4 ps = psv[dt * 4 + g4];
;       const u32x2 z = zv[dt * 4 + g4];
;       u32x2 v;
;       v[0] = pk2(acc[dt][4 * g4] * ps[0] * siluf_(lo16(z[0])), acc[dt][4 * g4 + 1] * ps[1] * siluf_(hi16(z[0])));
;       v[1] = pk2(acc[dt][4 * g4 + 2] * ps[2] * siluf_(lo16(z[1])), acc[dt][4 * g4 + 3] * ps[3] * siluf_(hi16(z[1])));
;       *(u32x2*)(y + tok * 1024 + 512 + col) = v;
;     }
	v_lshlrev_b32_e32 v18, 16, v92
	v_cvt_pk_bf16_f32 v1, v2, v3
	v_lshl_add_u64 v[2:3], v[94:95], 1, v[64:65]
	v_and_b32_e32 v19, 0xffff0000, v92
	global_store_dwordx2 v[2:3], v[0:1], off
	v_mul_f32_e32 v0, 0xbfb8aa3b, v18
	v_mul_f32_e32 v1, 0xbfb8aa3b, v19
	v_exp_f32_e32 v0, v0
	v_exp_f32_e32 v1, v1
	v_pk_mul_f32 v[2:3], v[40:41], v[4:5]
	v_pk_add_f32 v[0:1], v[0:1], 1.0 op_sel_hi:[1,0]
	s_nop 0
	v_div_scale_f32 v4, s[0:1], v1, v1, v19
	v_rcp_f32_e32 v5, v4
	s_nop 0
	v_fma_f32 v20, -v4, v5, 1.0
	v_fmac_f32_e32 v5, v20, v5
	v_div_scale_f32 v20, vcc, v19, v1, v19
	v_mul_f32_e32 v21, v20, v5
	v_fma_f32 v22, -v4, v21, v20
	v_fmac_f32_e32 v21, v22, v5
	v_fma_f32 v4, -v4, v21, v20
	v_div_fmas_f32 v4, v4, v5, v21
	v_div_fixup_f32 v1, v4, v1, v19
	v_div_scale_f32 v4, s[0:1], v0, v0, v18
	v_rcp_f32_e32 v5, v4
	s_nop 0
	v_fma_f32 v19, -v4, v5, 1.0
	v_fmac_f32_e32 v5, v19, v5
	v_div_scale_f32 v19, vcc, v18, v0, v18
	v_mul_f32_e32 v20, v19, v5
	v_fma_f32 v21, -v4, v20, v19
	v_fmac_f32_e32 v20, v21, v5
	v_fma_f32 v4, -v4, v20, v19
	v_div_fmas_f32 v4, v4, v5, v20
	v_div_fixup_f32 v0, v4, v0, v18
	v_pk_mul_f32 v[0:1], v[0:1], v[2:3]
	v_and_b32_e32 v18, 0xffff0000, v93
	v_cvt_pk_bf16_f32 v0, v0, v1
	v_lshlrev_b32_e32 v1, 16, v93
	v_mul_f32_e32 v2, 0xbfb8aa3b, v1
	v_mul_f32_e32 v3, 0xbfb8aa3b, v18
	v_exp_f32_e32 v2, v2
	v_exp_f32_e32 v3, v3
	v_pk_mul_f32 v[4:5], v[42:43], v[6:7]
	v_pk_add_f32 v[2:3], v[2:3], 1.0 op_sel_hi:[1,0]
	s_nop 0
	v_div_scale_f32 v6, s[0:1], v3, v3, v18
	v_rcp_f32_e32 v7, v6
	s_nop 0
	v_fma_f32 v19, -v6, v7, 1.0
	v_fmac_f32_e32 v7, v19, v7
	v_div_scale_f32 v19, vcc, v18, v3, v18
	v_mul_f32_e32 v20, v19, v7
	v_fma_f32 v21, -v6, v20, v19
	v_fmac_f32_e32 v20, v21, v7
	v_fma_f32 v6, -v6, v20, v19
	v_div_fmas_f32 v6, v6, v7, v20
	v_div_fixup_f32 v3, v6, v3, v18
	v_div_scale_f32 v6, s[0:1], v2, v2, v1
	v_rcp_f32_e32 v7, v6
	s_nop 0
	v_fma_f32 v18, -v6, v7, 1.0
	v_fmac_f32_e32 v7, v18, v7
	v_div_scale_f32 v18, vcc, v1, v2, v1
	v_mul_f32_e32 v19, v18, v7
	v_fma_f32 v20, -v6, v19, v18
	v_fmac_f32_e32 v19, v20, v7
	v_fma_f32 v6, -v6, v19, v18
	v_div_fmas_f32 v6, v6, v7, v19
	v_div_fixup_f32 v2, v6, v2, v1
	v_pk_mul_f32 v[2:3], v[2:3], v[4:5]
	s_waitcnt vmcnt(6)
	v_lshlrev_b32_e32 v4, 16, v90
	v_cvt_pk_bf16_f32 v1, v2, v3
	v_and_b32_e32 v5, 0xffff0000, v90
	global_store_dwordx2 v[16:17], v[0:1], off offset:80
	v_mul_f32_e32 v0, 0xbfb8aa3b, v4
	v_mul_f32_e32 v1, 0xbfb8aa3b, v5
	v_exp_f32_e32 v0, v0
	v_exp_f32_e32 v1, v1
	v_pk_mul_f32 v[2:3], v[36:37], v[8:9]
	v_pk_add_f32 v[0:1], v[0:1], 1.0 op_sel_hi:[1,0]
	s_nop 0
	v_div_scale_f32 v6, s[0:1], v1, v1, v5
	v_rcp_f32_e32 v7, v6
	s_nop 0
	v_fma_f32 v8, -v6, v7, 1.0
	v_fmac_f32_e32 v7, v8, v7
	v_div_scale_f32 v8, vcc, v5, v1, v5
	v_mul_f32_e32 v9, v8, v7
	v_fma_f32 v18, -v6, v9, v8
	v_fmac_f32_e32 v9, v18, v7
	v_fma_f32 v6, -v6, v9, v8
	v_div_fmas_f32 v6, v6, v7, v9
	v_div_fixup_f32 v1, v6, v1, v5
	v_div_scale_f32 v5, s[0:1], v0, v0, v4
	v_rcp_f32_e32 v6, v5
	s_nop 0
	v_fma_f32 v7, -v5, v6, 1.0
	v_fmac_f32_e32 v6, v7, v6
	v_div_scale_f32 v7, vcc, v4, v0, v4
	v_mul_f32_e32 v8, v7, v6
	v_fma_f32 v9, -v5, v8, v7
	v_fmac_f32_e32 v8, v9, v6
	v_fma_f32 v5, -v5, v8, v7
	v_div_fmas_f32 v5, v5, v6, v8
	v_div_fixup_f32 v0, v5, v0, v4
	v_pk_mul_f32 v[0:1], v[0:1], v[2:3]
	v_and_b32_e32 v6, 0xffff0000, v91
	v_cvt_pk_bf16_f32 v0, v0, v1
	v_lshlrev_b32_e32 v1, 16, v91
	v_mul_f32_e32 v2, 0xbfb8aa3b, v1
	v_mul_f32_e32 v3, 0xbfb8aa3b, v6
	v_exp_f32_e32 v2, v2
	v_exp_f32_e32 v3, v3
	v_pk_mul_f32 v[4:5], v[38:39], v[10:11]
	v_pk_add_f32 v[2:3], v[2:3], 1.0 op_sel_hi:[1,0]
	s_nop 0
	v_div_scale_f32 v7, s[0:1], v3, v3, v6
	v_rcp_f32_e32 v8, v7
	s_nop 0
	v_fma_f32 v9, -v7, v8, 1.0
	v_fmac_f32_e32 v8, v9, v8
	v_div_scale_f32 v9, vcc, v6, v3, v6
	v_mul_f32_e32 v10, v9, v8
	v_fma_f32 v11, -v7, v10, v9
	v_fmac_f32_e32 v10, v11, v8
	v_fma_f32 v7, -v7, v10, v9
	v_div_fmas_f32 v7, v7, v8, v10
	v_div_fixup_f32 v3, v7, v3, v6
	v_div_scale_f32 v6, s[0:1], v2, v2, v1
	v_rcp_f32_e32 v7, v6
	s_nop 0
	v_fma_f32 v8, -v6, v7, 1.0
	v_fmac_f32_e32 v7, v8, v7
	v_div_scale_f32 v8, vcc, v1, v2, v1
	v_mul_f32_e32 v9, v8, v7
	v_fma_f32 v10, -v6, v9, v8
	v_fmac_f32_e32 v9, v10, v7
	v_fma_f32 v6, -v6, v9, v8
	v_div_fmas_f32 v6, v6, v7, v9
	v_div_fixup_f32 v2, v6, v2, v1
	v_pk_mul_f32 v[2:3], v[2:3], v[4:5]
	s_waitcnt vmcnt(6)
; DI char* opq(char* q) { size_t z = 0; asm volatile("" : "+s"(z)); return q + z; }
; DI float lo16(unsigned w) { return __uint_as_float(w << 16); }
; DI float hi16(unsigned w) { return __uint_as_float(w & 0xffff0000u); }
; DI float siluf_(float x) { return x / (1.f + __expf(-x)); }
; DI void pool_item(const Params& p, int l, int it, char* lds) {
;     ...
;   u16* y = (u16*)(ws_ + OFF_XB);
; #pragma unroll
;   for (int dt = 0; dt < 2; ++dt)
; #pragma unroll
;     for (int g4 = 0; g4 < 4; ++g4) {
;       const int col = g * 64 + dt * 32 + 8 * g4 + 4 * hi;
;       const f32x4 ps = psv[dt * 4 + g4];
;       const u32x2 z = zv[dt * 4 + g4];
;       u32x2 v;
;       v[0] = pk2(acc[dt][4 * g4] * ps[0] * siluf_(lo16(z[0])), acc[dt][4 * g4 + 1] * ps[1] * siluf_(hi16(z[0])));
;       v[1] = pk2(acc[dt][4 * g4 + 2] * ps[2] * siluf_(lo16(z[1])), acc[dt][4 * g4 + 3] * ps[3] * siluf_(hi16(z[1])));
;       *(u32x2*)(y + tok * 1024 + 512 + col) = v;
;     }
; DI void dilcomb_item(const Params& p, int it) {
;   char* const ws_ = opq(p.ws);
;   const u16* proj = (const u16*)(ws_ + OFF_PROJ);
;   const u16* od = (const u16*)(ws_ + OFF_ODIL);
;   const float* lse = (const float*)(ws_ + OFF_LSE);
;   u16* y = (u16*)(ws_ + OFF_XB);
; #pragma unroll
;   for (int i = 0; i < 4; ++i) {
;     const int idx = it * 1024 + i * 256 + threadIdx.x;
;     const size_t tok = idx >> 5; const int c8 = idx & 31, h = c8 >> 3;
;     const float l0 = lse[((size_t)0 * T_ + tok) * 4 + h], l1 = lse[((size_t)1 * T_ + tok) * 4 + h], l2 = lse[((size_t)2 * T_ + tok) * 4 + h];
;     const float mx = fmaxf(l0, fmaxf(l1, l2));
;     float w0 = __expf(l0 - mx), w1 = __expf(l1 - mx), w2 = __expf(l2 - mx);
;     const float iw = 1.f / (w0 + w1 + w2); w0 *= iw; w1 *= iw; w2 *= iw;
;     const u32x4 a = *(const u32x4*)(od + ((size_t)0 * T_ + tok) * 256 + c8 * 8), bq = *(const u32x4*)(od + ((size_t)1 * T_ + tok) * 256 + c8 * 8), cq = *(const u32x4*)(od + ((size_t)2 * T_ + tok) * 256 + c8 * 8);
;     const u32x4 z = *(const u32x4*)(proj + tok * NP + C_BZ + c8 * 8);
	v_lshlrev_b32_e32 v4, 16, v88
	v_cvt_pk_bf16_f32 v1, v2, v3
	v_and_b32_e32 v5, 0xffff0000, v88
	global_store_dwordx2 v[16:17], v[0:1], off offset:96
	v_mul_f32_e32 v0, 0xbfb8aa3b, v4
	v_mul_f32_e32 v1, 0xbfb8aa3b, v5
	v_exp_f32_e32 v0, v0
	v_exp_f32_e32 v1, v1
	v_pk_mul_f32 v[2:3], v[32:33], v[12:13]
	v_pk_add_f32 v[0:1], v[0:1], 1.0 op_sel_hi:[1,0]
	s_nop 0
	v_div_scale_f32 v6, s[0:1], v1, v1, v5
	v_rcp_f32_e32 v7, v6
	s_nop 0
	v_fma_f32 v8, -v6, v7, 1.0
	v_fmac_f32_e32 v7, v8, v7
	v_div_scale_f32 v8, vcc, v5, v1, v5
	v_mul_f32_e32 v9, v8, v7
	v_fma_f32 v10, -v6, v9, v8
	v_fmac_f32_e32 v9, v10, v7
	v_fma_f32 v6, -v6, v9, v8
	v_div_fmas_f32 v6, v6, v7, v9
	v_div_fixup_f32 v1, v6, v1, v5
	v_div_scale_f32 v5, s[0:1], v0, v0, v4
	v_rcp_f32_e32 v6, v5
	s_nop 0
	v_fma_f32 v7, -v5, v6, 1.0
	v_fmac_f32_e32 v6, v7, v6
	v_div_scale_f32 v7, vcc, v4, v0, v4
	v_mul_f32_e32 v8, v7, v6
	v_fma_f32 v9, -v5, v8, v7
	v_fmac_f32_e32 v8, v9, v6
	v_fma_f32 v5, -v5, v8, v7
	v_div_fmas_f32 v5, v5, v6, v8
	v_div_fixup_f32 v0, v5, v0, v4
	v_pk_mul_f32 v[0:1], v[0:1], v[2:3]
	v_and_b32_e32 v6, 0xffff0000, v89
	v_cvt_pk_bf16_f32 v0, v0, v1
	v_lshlrev_b32_e32 v1, 16, v89
	v_mul_f32_e32 v2, 0xbfb8aa3b, v1
	v_mul_f32_e32 v3, 0xbfb8aa3b, v6
	v_exp_f32_e32 v2, v2
	v_exp_f32_e32 v3, v3
	v_pk_mul_f32 v[4:5], v[34:35], v[14:15]
	v_pk_add_f32 v[2:3], v[2:3], 1.0 op_sel_hi:[1,0]
	s_nop 0
	v_div_scale_f32 v7, s[0:1], v3, v3, v6
	v_rcp_f32_e32 v8, v7
	s_nop 0
	v_fma_f32 v9, -v7, v8, 1.0
	v_fmac_f32_e32 v8, v9, v8
	v_div_scale_f32 v9, vcc, v6, v3, v6
	v_mul_f32_e32 v10, v9, v8
	v_fma_f32 v11, -v7, v10, v9
	v_fmac_f32_e32 v10, v11, v8
	v_fma_f32 v7, -v7, v10, v9
	v_div_fmas_f32 v7, v7, v8, v10
	v_div_fixup_f32 v3, v7, v3, v6
	v_div_scale_f32 v6, s[0:1], v2, v2, v1
	v_rcp_f32_e32 v7, v6
	s_mov_b64 s[0:1], 0
	v_fma_f32 v8, -v6, v7, 1.0
	v_fmac_f32_e32 v7, v8, v7
	v_div_scale_f32 v8, vcc, v1, v2, v1
	v_mul_f32_e32 v9, v8, v7
	v_fma_f32 v10, -v6, v9, v8
	v_fmac_f32_e32 v9, v10, v7
	v_fma_f32 v6, -v6, v9, v8
	v_div_fmas_f32 v6, v6, v7, v9
	v_div_fixup_f32 v2, v6, v2, v1
	v_pk_mul_f32 v[2:3], v[2:3], v[4:5]
	s_nop 0
	v_cvt_pk_bf16_f32 v1, v2, v3
	global_store_dwordx2 v[16:17], v[0:1], off offset:112
	v_add_u32_e32 v0, s14, v119
	s_add_u32 s0, s90, s0
	s_addc_u32 s1, s91, s1
	v_lshl_or_b32 v31, v0, 10, v176
	v_lshl_add_u64 v[0:1], s[0:1], 0, v[182:183]
	v_ashrrev_i32_e32 v12, 5, v31
	v_lshl_add_u64 v[18:19], v[0:1], 0, s[2:3]
	v_lshl_add_u64 v[0:1], s[0:1], 0, v[184:185]
	v_ashrrev_i32_e32 v13, 31, v12
	v_lshl_add_u64 v[16:17], v[0:1], 0, s[94:95]
	v_lshl_add_u64 v[0:1], v[12:13], 4, v[18:19]
	v_lshl_add_u64 v[4:5], v[12:13], 0, s[96:97]
	global_load_dword v2, v[0:1], off
	v_lshl_add_u64 v[0:1], v[4:5], 4, v[18:19]
	v_lshl_add_u64 v[6:7], v[12:13], 0, s[4:5]
	global_load_dword v3, v[0:1], off
	v_lshl_add_u64 v[0:1], v[6:7], 4, v[18:19]
	global_load_dword v0, v[0:1], off
	v_mov_b64_e32 v[20:21], s[0:1]
	v_lshlrev_b64 v[4:5], 9, v[4:5]
	v_mad_i64_i32 v[22:23], s[0:1], v12, s33, v[20:21]
	v_lshl_add_u64 v[4:5], v[16:17], 0, v[4:5]
	v_lshl_add_u64 v[26:27], v[22:23], 0, v[184:185]
	s_add_i32 s6, s6, 1
	v_mov_b32_e32 v168, s93
	v_mov_b32_e32 v169, 0
	v_mov_b32_e32 v161, 0
	v_add_u32_e32 v160, 0x100, v31
	v_ashrrev_i32_e32 v160, 5, v160
	v_lshl_add_u64 v[162:163], v[160:161], 0, s[96:97]
	v_lshl_add_u64 v[164:165], v[160:161], 0, s[4:5]
	v_lshl_add_u64 v[166:167], v[160:161], 4, v[18:19]
	global_load_dword v150, v[166:167], off
	v_lshl_add_u64 v[166:167], v[162:163], 4, v[18:19]
	global_load_dword v151, v[166:167], off
	v_lshl_add_u64 v[166:167], v[164:165], 4, v[18:19]
	global_load_dword v152, v[166:167], off
	v_lshl_add_u64 v[162:163], v[160:161], 0, s[96:97]
	v_lshl_add_u64 v[164:165], v[160:161], 0, s[4:5]
	v_lshlrev_b64 v[166:167], 9, v[160:161]
	v_lshl_add_u64 v[166:167], v[16:17], 0, v[166:167]
	global_load_dwordx4 v[56:59], v[166:167], off
	v_lshlrev_b64 v[166:167], 9, v[162:163]
	v_lshl_add_u64 v[166:167], v[16:17], 0, v[166:167]
	global_load_dwordx4 v[60:63], v[166:167], off
	v_lshlrev_b64 v[166:167], 9, v[164:165]
	v_lshl_add_u64 v[166:167], v[16:17], 0, v[166:167]
	global_load_dwordx4 v[100:103], v[166:167], off
	v_mad_i64_i32 v[166:167], s[0:1], v160, s33, v[20:21]
	v_lshl_add_u64 v[166:167], v[166:167], 0, v[184:185]
	v_lshl_add_u64 v[166:167], v[166:167], 0, v[168:169]
	global_load_dwordx4 v[104:107], v[166:167], off offset:3328
	v_add_u32_e32 v160, 0x200, v31
	v_ashrrev_i32_e32 v160, 5, v160
	v_lshl_add_u64 v[162:163], v[160:161], 0, s[96:97]
	v_lshl_add_u64 v[164:165], v[160:161], 0, s[4:5]
	v_lshl_add_u64 v[166:167], v[160:161], 4, v[18:19]
	global_load_dword v153, v[166:167], off
	v_lshl_add_u64 v[166:167], v[162:163], 4, v[18:19]
	global_load_dword v154, v[166:167], off
	v_lshl_add_u64 v[166:167], v[164:165], 4, v[18:19]
	global_load_dword v155, v[166:167], off
	v_lshl_add_u64 v[162:163], v[160:161], 0, s[96:97]
	v_lshl_add_u64 v[164:165], v[160:161], 0, s[4:5]
	v_lshlrev_b64 v[166:167], 9, v[160:161]
	v_lshl_add_u64 v[166:167], v[16:17], 0, v[166:167]
	global_load_dwordx4 v[108:111], v[166:167], off
	v_lshlrev_b64 v[166:167], 9, v[162:163]
	v_lshl_add_u64 v[166:167], v[16:17], 0, v[166:167]
	global_load_dwordx4 v[112:115], v[166:167], off
	v_lshlrev_b64 v[166:167], 9, v[164:165]
	v_lshl_add_u64 v[166:167], v[16:17], 0, v[166:167]
	global_load_dwordx4 v[120:123], v[166:167], off
	v_mad_i64_i32 v[166:167], s[0:1], v160, s33, v[20:21]
	v_lshl_add_u64 v[166:167], v[166:167], 0, v[184:185]
	v_lshl_add_u64 v[166:167], v[166:167], 0, v[168:169]
	global_load_dwordx4 v[124:127], v[166:167], off offset:3328
	v_add_u32_e32 v160, 0x300, v31
	v_ashrrev_i32_e32 v160, 5, v160
; DI float lo16(unsigned w) { return __uint_as_float(w << 16); }
; DI float hi16(unsigned w) { return __uint_as_float(w & 0xffff0000u); }
; DI float siluf_(float x) { return x / (1.f + __expf(-x)); }
; DI void dilcomb_item(const Params& p, int it) {
;     ...
;   for (int i = 0; i < 4; ++i) {
;     const int idx = it * 1024 + i * 256 + threadIdx.x;
;     const size_t tok = idx >> 5; const int c8 = idx & 31, h = c8 >> 3;
;     const float l0 = lse[((size_t)0 * T_ + tok) * 4 + h], l1 = lse[((size_t)1 * T_ + tok) * 4 + h], l2 = lse[((size_t)2 * T_ + tok) * 4 + h];
;     const float mx = fmaxf(l0, fmaxf(l1, l2));
;     float w0 = __expf(l0 - mx), w1 = __expf(l1 - mx), w2 = __expf(l2 - mx);
;     const float iw = 1.f / (w0 + w1 + w2); w0 *= iw; w1 *= iw; w2 *= iw;
;     const u32x4 a = *(const u32x4*)(od + ((size_t)0 * T_ + tok) * 256 + c8 * 8), bq = *(const u32x4*)(od + ((size_t)1 * T_ + tok) * 256 + c8 * 8), cq = *(const u32x4*)(od + ((size_t)2 * T_ + tok) * 256 + c8 * 8);
;     const u32x4 z = *(const u32x4*)(proj + tok * NP + C_BZ + c8 * 8);
;     u32x4 r;
; #pragma unroll
;     for (int e = 0; e < 4; ++e) {
;       const float v0 = (w0 * lo16(a[e]) + w1 * lo16(bq[e]) + w2 * lo16(cq[e])) * siluf_(lo16(z[e]));
;       const float v1 = (w0 * hi16(a[e]) + w1 * hi16(bq[e]) + w2 * hi16(cq[e])) * siluf_(hi16(z[e]));
;       r[e] = pk2(v0, v1);
;     }
;     *(u32x4*)(y + tok * 1024 + 256 + c8 * 8) = r;
	v_lshl_add_u64 v[162:163], v[160:161], 0, s[96:97]
	v_lshl_add_u64 v[164:165], v[160:161], 0, s[4:5]
	v_lshl_add_u64 v[166:167], v[160:161], 4, v[18:19]
	global_load_dword v156, v[166:167], off
	v_lshl_add_u64 v[166:167], v[162:163], 4, v[18:19]
	global_load_dword v157, v[166:167], off
	v_lshl_add_u64 v[166:167], v[164:165], 4, v[18:19]
	global_load_dword v158, v[166:167], off
	v_lshl_add_u64 v[162:163], v[160:161], 0, s[96:97]
	v_lshl_add_u64 v[164:165], v[160:161], 0, s[4:5]
	v_lshlrev_b64 v[166:167], 9, v[160:161]
	v_lshl_add_u64 v[166:167], v[16:17], 0, v[166:167]
	global_load_dwordx4 v[128:131], v[166:167], off
	v_lshlrev_b64 v[166:167], 9, v[162:163]
	v_lshl_add_u64 v[166:167], v[16:17], 0, v[166:167]
	global_load_dwordx4 v[132:135], v[166:167], off
	v_lshlrev_b64 v[166:167], 9, v[164:165]
	v_lshl_add_u64 v[166:167], v[16:17], 0, v[166:167]
	global_load_dwordx4 v[136:139], v[166:167], off
	v_mad_i64_i32 v[166:167], s[0:1], v160, s33, v[20:21]
	v_lshl_add_u64 v[166:167], v[166:167], 0, v[184:185]
	v_lshl_add_u64 v[166:167], v[166:167], 0, v[168:169]
	global_load_dwordx4 v[140:143], v[166:167], off offset:3328
	v_lshl_add_u64 v[162:163], v[12:13], 0, s[96:97]
	v_lshl_add_u64 v[164:165], v[12:13], 0, s[4:5]
	v_lshlrev_b64 v[166:167], 9, v[12:13]
	v_lshl_add_u64 v[166:167], v[16:17], 0, v[166:167]
	global_load_dwordx4 v[40:43], v[166:167], off
	v_lshlrev_b64 v[166:167], 9, v[162:163]
	v_lshl_add_u64 v[166:167], v[16:17], 0, v[166:167]
	global_load_dwordx4 v[44:47], v[166:167], off
	v_lshlrev_b64 v[166:167], 9, v[164:165]
	v_lshl_add_u64 v[166:167], v[16:17], 0, v[166:167]
	global_load_dwordx4 v[48:51], v[166:167], off
	v_mad_i64_i32 v[166:167], s[0:1], v12, s33, v[20:21]
	v_lshl_add_u64 v[166:167], v[166:167], 0, v[184:185]
	v_lshl_add_u64 v[166:167], v[166:167], 0, v[168:169]
	global_load_dwordx4 v[52:55], v[166:167], off offset:3328
	s_waitcnt vmcnt(0)
	v_max3_f32 v1, v2, v3, v0
	v_sub_f32_e32 v2, v2, v1
	v_mul_f32_e32 v2, 0x3fb8aa3b, v2
	v_exp_f32_e32 v25, v2
	v_sub_f32_e32 v2, v3, v1
	v_mul_f32_e32 v2, 0x3fb8aa3b, v2
	v_sub_f32_e32 v0, v0, v1
	v_exp_f32_e32 v24, v2
	v_mul_f32_e32 v0, 0x3fb8aa3b, v0
	v_exp_f32_e32 v0, v0
	v_add_f32_e32 v1, v25, v24
	v_add_f32_e32 v1, v0, v1
	v_div_scale_f32 v2, s[2:3], v1, v1, 1.0
	v_rcp_f32_e32 v3, v2
	s_nop 0
	v_fma_f32 v8, -v2, v3, 1.0
	v_fmac_f32_e32 v3, v8, v3
	v_div_scale_f32 v8, vcc, 1.0, v1, 1.0
	v_mul_f32_e32 v9, v8, v3
	v_fma_f32 v10, -v2, v9, v8
	v_fmac_f32_e32 v9, v10, v3
	v_fma_f32 v2, -v2, v9, v8
	v_div_fmas_f32 v2, v2, v3, v9
	v_div_fixup_f32 v30, v2, v1, 1.0
	v_mul_f32_e32 v14, v0, v30
	v_lshlrev_b64 v[0:1], 9, v[12:13]
	v_lshl_add_u64 v[0:1], v[16:17], 0, v[0:1]
	v_mov_b32_e32 v0, v40
	v_mov_b32_e32 v1, v41
	v_mov_b32_e32 v2, v42
	v_mov_b32_e32 v3, v43
	v_add_co_u32_e32 v26, vcc, s93, v26
	v_mov_b32_e32 v8, v44
	v_mov_b32_e32 v9, v45
	v_mov_b32_e32 v10, v46
	v_mov_b32_e32 v11, v47
	v_lshlrev_b64 v[4:5], 9, v[6:7]
	v_lshl_add_u64 v[4:5], v[16:17], 0, v[4:5]
	v_addc_co_u32_e32 v27, vcc, 0, v27, vcc
	v_mov_b32_e32 v4, v48
	v_mov_b32_e32 v5, v49
	v_mov_b32_e32 v6, v50
	v_mov_b32_e32 v7, v51
	v_pk_mul_f32 v[24:25], v[24:25], v[30:31] op_sel_hi:[1,0]
	v_mov_b32_e32 v26, v52
	v_mov_b32_e32 v27, v53
	v_mov_b32_e32 v28, v54
	v_mov_b32_e32 v29, v55
	v_and_b32_e32 v35, 0xffff0000, v0
	v_lshlrev_b32_e32 v36, 16, v0
	v_lshlrev_b32_e32 v34, 16, v8
	v_and_b32_e32 v37, 0xffff0000, v8
	v_pk_mul_f32 v[36:37], v[24:25], v[36:37] op_sel:[1,0] op_sel_hi:[0,1]
	v_pk_fma_f32 v[34:35], v[24:25], v[34:35], v[36:37]
	v_lshlrev_b32_e32 v38, 16, v4
	v_and_b32_e32 v39, 0xffff0000, v4
	v_lshlrev_b32_e32 v13, 16, v26
	v_and_b32_e32 v15, 0xffff0000, v26
	v_mul_f32_e32 v26, 0xbfb8aa3b, v13
	v_mul_f32_e32 v0, 0xbfb8aa3b, v15
	v_exp_f32_e32 v32, v26
	v_exp_f32_e32 v33, v0
	s_nop 0
	v_pk_add_f32 v[32:33], v[32:33], 1.0 op_sel_hi:[1,0]
	s_nop 0
	v_div_scale_f32 v0, s[0:1], v33, v33, v15
	v_rcp_f32_e32 v4, v0
	s_nop 0
	v_fma_f32 v8, -v0, v4, 1.0
	v_fmac_f32_e32 v4, v8, v4
	v_div_scale_f32 v8, vcc, v15, v33, v15
	v_mul_f32_e32 v26, v8, v4
	v_fma_f32 v30, -v0, v26, v8
	v_fmac_f32_e32 v26, v30, v4
	v_fma_f32 v0, -v0, v26, v8
	v_div_fmas_f32 v0, v0, v4, v26
	v_div_fixup_f32 v33, v0, v33, v15
	v_div_scale_f32 v0, s[0:1], v32, v32, v13
	v_rcp_f32_e32 v4, v0
	s_nop 0
	v_fma_f32 v8, -v0, v4, 1.0
	v_fmac_f32_e32 v4, v8, v4
	v_div_scale_f32 v8, vcc, v13, v32, v13
	v_mul_f32_e32 v15, v8, v4
	v_fma_f32 v26, -v0, v15, v8
	v_fmac_f32_e32 v15, v26, v4
	v_fma_f32 v0, -v0, v15, v8
	v_div_fmas_f32 v0, v0, v4, v15
	v_div_fixup_f32 v32, v0, v32, v13
	v_pk_fma_f32 v[34:35], v[14:15], v[38:39], v[34:35] op_sel_hi:[0,1,1]
	v_lshlrev_b32_e32 v13, 16, v27
	v_and_b32_e32 v15, 0xffff0000, v27
	v_pk_mul_f32 v[32:33], v[32:33], v[34:35]
	v_mul_f32_e32 v4, 0xbfb8aa3b, v13
	v_and_b32_e32 v27, 0xffff0000, v1
	v_lshlrev_b32_e32 v8, 16, v1
	v_mul_f32_e32 v1, 0xbfb8aa3b, v15
	v_cvt_pk_bf16_f32 v0, v32, v33
	v_exp_f32_e32 v4, v4
	v_lshlrev_b32_e32 v32, 16, v5
	v_and_b32_e32 v33, 0xffff0000, v5
	v_exp_f32_e32 v5, v1
	v_lshlrev_b32_e32 v26, 16, v9
	v_and_b32_e32 v9, 0xffff0000, v9
	v_pk_mul_f32 v[8:9], v[24:25], v[8:9] op_sel:[1,0] op_sel_hi:[0,1]
	v_pk_add_f32 v[4:5], v[4:5], 1.0 op_sel_hi:[1,0]
	v_pk_fma_f32 v[8:9], v[24:25], v[26:27], v[8:9]
	v_div_scale_f32 v1, s[0:1], v5, v5, v15
	v_rcp_f32_e32 v30, v1
	v_lshlrev_b32_e32 v26, 16, v2
	v_and_b32_e32 v27, 0xffff0000, v10
	v_pk_mul_f32 v[26:27], v[24:25], v[26:27] op_sel:[1,0] op_sel_hi:[0,1]
	v_fma_f32 v34, -v1, v30, 1.0
	v_fmac_f32_e32 v30, v34, v30
	v_div_scale_f32 v34, vcc, v15, v5, v15
	v_mul_f32_e32 v35, v34, v30
	v_fma_f32 v36, -v1, v35, v34
	v_fmac_f32_e32 v35, v36, v30
	v_fma_f32 v1, -v1, v35, v34
; DI float lo16(unsigned w) { return __uint_as_float(w << 16); }
; DI float hi16(unsigned w) { return __uint_as_float(w & 0xffff0000u); }
; DI float siluf_(float x) { return x / (1.f + __expf(-x)); }
; DI void dilcomb_item(const Params& p, int it) {
;     ...
;   for (int i = 0; i < 4; ++i) {
;     const int idx = it * 1024 + i * 256 + threadIdx.x;
;     const size_t tok = idx >> 5; const int c8 = idx & 31, h = c8 >> 3;
;     const float l0 = lse[((size_t)0 * T_ + tok) * 4 + h], l1 = lse[((size_t)1 * T_ + tok) * 4 + h], l2 = lse[((size_t)2 * T_ + tok) * 4 + h];
;     const float mx = fmaxf(l0, fmaxf(l1, l2));
;     float w0 = __expf(l0 - mx), w1 = __expf(l1 - mx), w2 = __expf(l2 - mx);
;     const float iw = 1.f / (w0 + w1 + w2); w0 *= iw; w1 *= iw; w2 *= iw;
;     const u32x4 a = *(const u32x4*)(od + ((size_t)0 * T_ + tok) * 256 + c8 * 8), bq = *(const u32x4*)(od + ((size_t)1 * T_ + tok) * 256 + c8 * 8), cq = *(const u32x4*)(od + ((size_t)2 * T_ + tok) * 256 + c8 * 8);
;     const u32x4 z = *(const u32x4*)(proj + tok * NP + C_BZ + c8 * 8);
;     u32x4 r;
; #pragma unroll
;     for (int e = 0; e < 4; ++e) {
;       const float v0 = (w0 * lo16(a[e]) + w1 * lo16(bq[e]) + w2 * lo16(cq[e])) * siluf_(lo16(z[e]));
;       const float v1 = (w0 * hi16(a[e]) + w1 * hi16(bq[e]) + w2 * hi16(cq[e])) * siluf_(hi16(z[e]));
;       r[e] = pk2(v0, v1);
;     }
;     *(u32x4*)(y + tok * 1024 + 256 + c8 * 8) = r;
	v_div_fmas_f32 v1, v1, v30, v35
	v_div_fixup_f32 v5, v1, v5, v15
	v_div_scale_f32 v1, s[0:1], v4, v4, v13
	v_rcp_f32_e32 v15, v1
	s_nop 0
	v_fma_f32 v30, -v1, v15, 1.0
	v_fmac_f32_e32 v15, v30, v15
	v_div_scale_f32 v30, vcc, v13, v4, v13
	v_mul_f32_e32 v34, v30, v15
	v_fma_f32 v35, -v1, v34, v30
	v_fmac_f32_e32 v34, v35, v15
	v_fma_f32 v1, -v1, v34, v30
	v_div_fmas_f32 v1, v1, v15, v34
	v_div_fixup_f32 v4, v1, v4, v13
	v_pk_fma_f32 v[8:9], v[14:15], v[32:33], v[8:9] op_sel_hi:[0,1,1]
	v_pk_mul_f32 v[4:5], v[4:5], v[8:9]
	v_lshlrev_b32_e32 v13, 16, v28
	v_and_b32_e32 v15, 0xffff0000, v28
	v_cvt_pk_bf16_f32 v1, v4, v5
	v_mul_f32_e32 v4, 0xbfb8aa3b, v13
	v_and_b32_e32 v9, 0xffff0000, v2
	v_mul_f32_e32 v2, 0xbfb8aa3b, v15
	v_exp_f32_e32 v4, v4
	v_exp_f32_e32 v5, v2
	v_lshlrev_b32_e32 v32, 16, v6
	v_and_b32_e32 v33, 0xffff0000, v6
	v_lshlrev_b32_e32 v8, 16, v10
	v_pk_add_f32 v[4:5], v[4:5], 1.0 op_sel_hi:[1,0]
	v_pk_fma_f32 v[8:9], v[24:25], v[8:9], v[26:27]
	v_div_scale_f32 v2, s[0:1], v5, v5, v15
	v_rcp_f32_e32 v6, v2
	s_nop 0
	v_fma_f32 v10, -v2, v6, 1.0
	v_fmac_f32_e32 v6, v10, v6
	v_div_scale_f32 v10, vcc, v15, v5, v15
	v_mul_f32_e32 v28, v10, v6
	v_fma_f32 v30, -v2, v28, v10
	v_fmac_f32_e32 v28, v30, v6
	v_fma_f32 v2, -v2, v28, v10
	v_div_fmas_f32 v2, v2, v6, v28
	v_div_fixup_f32 v5, v2, v5, v15
	v_div_scale_f32 v2, s[0:1], v4, v4, v13
	v_rcp_f32_e32 v6, v2
	s_nop 0
	v_fma_f32 v10, -v2, v6, 1.0
	v_fmac_f32_e32 v6, v10, v6
	v_div_scale_f32 v10, vcc, v13, v4, v13
	v_mul_f32_e32 v15, v10, v6
	v_fma_f32 v28, -v2, v15, v10
	v_fmac_f32_e32 v15, v28, v6
	v_fma_f32 v2, -v2, v15, v10
	v_div_fmas_f32 v2, v2, v6, v15
	v_div_fixup_f32 v4, v2, v4, v13
	v_pk_fma_f32 v[8:9], v[14:15], v[32:33], v[8:9] op_sel_hi:[0,1,1]
	v_pk_mul_f32 v[4:5], v[4:5], v[8:9]
	v_lshlrev_b32_e32 v13, 16, v29
	v_and_b32_e32 v15, 0xffff0000, v29
	v_cvt_pk_bf16_f32 v2, v4, v5
	v_mul_f32_e32 v4, 0xbfb8aa3b, v13
	v_and_b32_e32 v9, 0xffff0000, v3
	v_lshlrev_b32_e32 v10, 16, v3
	v_mul_f32_e32 v3, 0xbfb8aa3b, v15
	v_exp_f32_e32 v4, v4
	v_exp_f32_e32 v5, v3
	v_lshlrev_b32_e32 v8, 16, v11
	v_and_b32_e32 v11, 0xffff0000, v11
	v_pk_mul_f32 v[10:11], v[24:25], v[10:11] op_sel:[1,0] op_sel_hi:[0,1]
	v_pk_add_f32 v[4:5], v[4:5], 1.0 op_sel_hi:[1,0]
	v_pk_fma_f32 v[8:9], v[24:25], v[8:9], v[10:11]
	v_lshlrev_b32_e32 v6, 16, v7
	v_and_b32_e32 v7, 0xffff0000, v7
	v_div_scale_f32 v3, s[0:1], v5, v5, v15
	v_pk_fma_f32 v[6:7], v[14:15], v[6:7], v[8:9] op_sel_hi:[0,1,1]
	v_rcp_f32_e32 v8, v3
	s_nop 0
	v_fma_f32 v9, -v3, v8, 1.0
	v_fmac_f32_e32 v8, v9, v8
	v_div_scale_f32 v9, vcc, v15, v5, v15
	v_mul_f32_e32 v10, v9, v8
	v_fma_f32 v11, -v3, v10, v9
	v_fmac_f32_e32 v10, v11, v8
	v_fma_f32 v3, -v3, v10, v9
	v_div_fmas_f32 v3, v3, v8, v10
	v_div_fixup_f32 v5, v3, v5, v15
	v_div_scale_f32 v3, s[0:1], v4, v4, v13
	v_rcp_f32_e32 v8, v3
	s_nop 0
	v_fma_f32 v9, -v3, v8, 1.0
	v_fmac_f32_e32 v8, v9, v8
	v_div_scale_f32 v9, vcc, v13, v4, v13
	v_mul_f32_e32 v10, v9, v8
	v_fma_f32 v11, -v3, v10, v9
	v_fmac_f32_e32 v10, v11, v8
	v_fma_f32 v3, -v3, v10, v9
	v_div_fmas_f32 v3, v3, v8, v10
	v_div_fixup_f32 v4, v3, v4, v13
	v_pk_mul_f32 v[4:5], v[4:5], v[6:7]
	s_nop 0
	v_cvt_pk_bf16_f32 v3, v4, v5
	v_mad_i64_i32 v[4:5], s[0:1], v12, s37, v[22:23]
	v_lshl_add_u64 v[4:5], v[4:5], 0, v[184:185]
	v_add_co_u32_e32 v4, vcc, s74, v4
	s_nop 1
	v_addc_co_u32_e32 v5, vcc, 0, v5, vcc
	global_store_dwordx4 v[4:5], v[0:3], off offset:512
	s_nop 1
	v_add_u32_e32 v0, 0x100, v31
	v_ashrrev_i32_e32 v22, 5, v0
	v_ashrrev_i32_e32 v23, 31, v22
	v_lshl_add_u64 v[0:1], v[22:23], 4, v[18:19]
	v_lshl_add_u64 v[4:5], v[22:23], 0, s[96:97]
	v_mov_b32_e32 v2, v150
	v_lshl_add_u64 v[0:1], v[4:5], 4, v[18:19]
	v_lshl_add_u64 v[6:7], v[22:23], 0, s[4:5]
	v_mov_b32_e32 v3, v151
	v_lshl_add_u64 v[0:1], v[6:7], 4, v[18:19]
	v_mov_b32_e32 v0, v152
	v_lshlrev_b64 v[4:5], 9, v[4:5]
	v_mad_i64_i32 v[26:27], s[0:1], v22, s33, v[20:21]
	v_lshl_add_u64 v[4:5], v[16:17], 0, v[4:5]
	v_lshl_add_u64 v[12:13], v[26:27], 0, v[184:185]
	v_max3_f32 v1, v2, v3, v0
	v_sub_f32_e32 v2, v2, v1
	v_mul_f32_e32 v2, 0x3fb8aa3b, v2
	v_exp_f32_e32 v29, v2
	v_sub_f32_e32 v2, v3, v1
	v_mul_f32_e32 v2, 0x3fb8aa3b, v2
	v_sub_f32_e32 v0, v0, v1
	v_exp_f32_e32 v28, v2
	v_mul_f32_e32 v0, 0x3fb8aa3b, v0
	v_exp_f32_e32 v0, v0
	v_add_f32_e32 v1, v29, v28
	v_add_f32_e32 v1, v0, v1
	v_div_scale_f32 v2, s[0:1], v1, v1, 1.0
	v_rcp_f32_e32 v3, v2
	s_nop 0
	v_fma_f32 v8, -v2, v3, 1.0
	v_fmac_f32_e32 v3, v8, v3
	v_div_scale_f32 v8, vcc, 1.0, v1, 1.0
	v_mul_f32_e32 v9, v8, v3
	v_fma_f32 v10, -v2, v9, v8
	v_fmac_f32_e32 v9, v10, v3
	v_fma_f32 v2, -v2, v9, v8
	v_div_fmas_f32 v2, v2, v3, v9
	v_div_fixup_f32 v30, v2, v1, 1.0
	v_mul_f32_e32 v24, v0, v30
	v_lshlrev_b64 v[0:1], 9, v[22:23]
	v_lshl_add_u64 v[0:1], v[16:17], 0, v[0:1]
	v_mov_b32_e32 v0, v56
	v_mov_b32_e32 v1, v57
	v_mov_b32_e32 v2, v58
	v_mov_b32_e32 v3, v59
	v_add_co_u32_e32 v12, vcc, s93, v12
	v_mov_b32_e32 v8, v60
	v_mov_b32_e32 v9, v61
	v_mov_b32_e32 v10, v62
	v_mov_b32_e32 v11, v63
	v_lshlrev_b64 v[4:5], 9, v[6:7]
	v_lshl_add_u64 v[4:5], v[16:17], 0, v[4:5]
	v_addc_co_u32_e32 v13, vcc, 0, v13, vcc
	v_mov_b32_e32 v4, v100
	v_mov_b32_e32 v5, v101
	v_mov_b32_e32 v6, v102
	v_mov_b32_e32 v7, v103
	v_pk_mul_f32 v[28:29], v[28:29], v[30:31] op_sel_hi:[1,0]
	v_mov_b32_e32 v12, v104
	v_mov_b32_e32 v13, v105
	v_mov_b32_e32 v14, v106
	v_mov_b32_e32 v15, v107
	v_and_b32_e32 v35, 0xffff0000, v0
	v_lshlrev_b32_e32 v36, 16, v0
	v_lshlrev_b32_e32 v34, 16, v8
	v_and_b32_e32 v37, 0xffff0000, v8
	v_pk_mul_f32 v[36:37], v[28:29], v[36:37] op_sel:[1,0] op_sel_hi:[0,1]
	v_pk_fma_f32 v[34:35], v[28:29], v[34:35], v[36:37]
	v_lshlrev_b32_e32 v38, 16, v4
; DI float lo16(unsigned w) { return __uint_as_float(w << 16); }
; DI float hi16(unsigned w) { return __uint_as_float(w & 0xffff0000u); }
; DI float siluf_(float x) { return x / (1.f + __expf(-x)); }
; DI void dilcomb_item(const Params& p, int it) {
;     ...
;   for (int i = 0; i < 4; ++i) {
;     const int idx = it * 1024 + i * 256 + threadIdx.x;
;     const size_t tok = idx >> 5; const int c8 = idx & 31, h = c8 >> 3;
;     const float l0 = lse[((size_t)0 * T_ + tok) * 4 + h], l1 = lse[((size_t)1 * T_ + tok) * 4 + h], l2 = lse[((size_t)2 * T_ + tok) * 4 + h];
;     const float mx = fmaxf(l0, fmaxf(l1, l2));
;     float w0 = __expf(l0 - mx), w1 = __expf(l1 - mx), w2 = __expf(l2 - mx);
;     const float iw = 1.f / (w0 + w1 + w2); w0 *= iw; w1 *= iw; w2 *= iw;
;     const u32x4 a = *(const u32x4*)(od + ((size_t)0 * T_ + tok) * 256 + c8 * 8), bq = *(const u32x4*)(od + ((size_t)1 * T_ + tok) * 256 + c8 * 8), cq = *(const u32x4*)(od + ((size_t)2 * T_ + tok) * 256 + c8 * 8);
;     const u32x4 z = *(const u32x4*)(proj + tok * NP + C_BZ + c8 * 8);
;     u32x4 r;
; #pragma unroll
;     for (int e = 0; e < 4; ++e) {
;       const float v0 = (w0 * lo16(a[e]) + w1 * lo16(bq[e]) + w2 * lo16(cq[e])) * siluf_(lo16(z[e]));
;       const float v1 = (w0 * hi16(a[e]) + w1 * hi16(bq[e]) + w2 * hi16(cq[e])) * siluf_(hi16(z[e]));
;       r[e] = pk2(v0, v1);
;     }
;     *(u32x4*)(y + tok * 1024 + 256 + c8 * 8) = r;
	v_and_b32_e32 v39, 0xffff0000, v4
	v_lshlrev_b32_e32 v23, 16, v12
	v_and_b32_e32 v12, 0xffff0000, v12
	v_mul_f32_e32 v25, 0xbfb8aa3b, v23
	v_mul_f32_e32 v0, 0xbfb8aa3b, v12
	v_exp_f32_e32 v32, v25
	v_exp_f32_e32 v33, v0
	s_nop 0
	v_pk_add_f32 v[32:33], v[32:33], 1.0 op_sel_hi:[1,0]
	s_nop 0
	v_div_scale_f32 v0, s[0:1], v33, v33, v12
	v_rcp_f32_e32 v4, v0
	s_nop 0
	v_fma_f32 v8, -v0, v4, 1.0
	v_fmac_f32_e32 v4, v8, v4
	v_div_scale_f32 v8, vcc, v12, v33, v12
	v_mul_f32_e32 v25, v8, v4
	v_fma_f32 v30, -v0, v25, v8
	v_fmac_f32_e32 v25, v30, v4
	v_fma_f32 v0, -v0, v25, v8
	v_div_fmas_f32 v0, v0, v4, v25
	v_div_fixup_f32 v33, v0, v33, v12
	v_div_scale_f32 v0, s[0:1], v32, v32, v23
	v_rcp_f32_e32 v4, v0
	s_nop 0
	v_fma_f32 v8, -v0, v4, 1.0
	v_fmac_f32_e32 v4, v8, v4
	v_div_scale_f32 v8, vcc, v23, v32, v23
	v_mul_f32_e32 v12, v8, v4
	v_fma_f32 v25, -v0, v12, v8
	v_fmac_f32_e32 v12, v25, v4
	v_fma_f32 v0, -v0, v12, v8
	v_div_fmas_f32 v0, v0, v4, v12
	v_div_fixup_f32 v32, v0, v32, v23
	v_pk_fma_f32 v[34:35], v[24:25], v[38:39], v[34:35] op_sel_hi:[0,1,1]
	v_lshlrev_b32_e32 v23, 16, v13
	v_and_b32_e32 v25, 0xffff0000, v13
	v_pk_mul_f32 v[32:33], v[32:33], v[34:35]
	v_mul_f32_e32 v4, 0xbfb8aa3b, v23
	v_and_b32_e32 v13, 0xffff0000, v1
	v_lshlrev_b32_e32 v8, 16, v1
	v_mul_f32_e32 v1, 0xbfb8aa3b, v25
	v_cvt_pk_bf16_f32 v0, v32, v33
	v_exp_f32_e32 v4, v4
	v_lshlrev_b32_e32 v32, 16, v5
	v_and_b32_e32 v33, 0xffff0000, v5
	v_exp_f32_e32 v5, v1
	v_lshlrev_b32_e32 v12, 16, v9
	v_and_b32_e32 v9, 0xffff0000, v9
	v_pk_mul_f32 v[8:9], v[28:29], v[8:9] op_sel:[1,0] op_sel_hi:[0,1]
	v_pk_add_f32 v[4:5], v[4:5], 1.0 op_sel_hi:[1,0]
	v_pk_fma_f32 v[8:9], v[28:29], v[12:13], v[8:9]
	v_div_scale_f32 v1, s[0:1], v5, v5, v25
	v_rcp_f32_e32 v30, v1
	v_lshlrev_b32_e32 v12, 16, v2
	v_and_b32_e32 v13, 0xffff0000, v10
	v_pk_mul_f32 v[12:13], v[28:29], v[12:13] op_sel:[1,0] op_sel_hi:[0,1]
	v_fma_f32 v34, -v1, v30, 1.0
	v_fmac_f32_e32 v30, v34, v30
	v_div_scale_f32 v34, vcc, v25, v5, v25
	v_mul_f32_e32 v35, v34, v30
	v_fma_f32 v36, -v1, v35, v34
	v_fmac_f32_e32 v35, v36, v30
	v_fma_f32 v1, -v1, v35, v34
	v_div_fmas_f32 v1, v1, v30, v35
	v_div_fixup_f32 v5, v1, v5, v25
	v_div_scale_f32 v1, s[0:1], v4, v4, v23
	v_rcp_f32_e32 v25, v1
	s_nop 0
	v_fma_f32 v30, -v1, v25, 1.0
	v_fmac_f32_e32 v25, v30, v25
	v_div_scale_f32 v30, vcc, v23, v4, v23
	v_mul_f32_e32 v34, v30, v25
	v_fma_f32 v35, -v1, v34, v30
	v_fmac_f32_e32 v34, v35, v25
	v_fma_f32 v1, -v1, v34, v30
	v_div_fmas_f32 v1, v1, v25, v34
	v_div_fixup_f32 v4, v1, v4, v23
	v_pk_fma_f32 v[8:9], v[24:25], v[32:33], v[8:9] op_sel_hi:[0,1,1]
	v_pk_mul_f32 v[4:5], v[4:5], v[8:9]
	v_lshlrev_b32_e32 v23, 16, v14
	v_and_b32_e32 v14, 0xffff0000, v14
	v_cvt_pk_bf16_f32 v1, v4, v5
	v_mul_f32_e32 v4, 0xbfb8aa3b, v23
	v_and_b32_e32 v9, 0xffff0000, v2
	v_mul_f32_e32 v2, 0xbfb8aa3b, v14
	v_exp_f32_e32 v4, v4
	v_exp_f32_e32 v5, v2
	v_lshlrev_b32_e32 v32, 16, v6
	v_and_b32_e32 v33, 0xffff0000, v6
	v_lshlrev_b32_e32 v8, 16, v10
	v_pk_add_f32 v[4:5], v[4:5], 1.0 op_sel_hi:[1,0]
	v_pk_fma_f32 v[8:9], v[28:29], v[8:9], v[12:13]
	v_div_scale_f32 v2, s[0:1], v5, v5, v14
	v_rcp_f32_e32 v6, v2
	v_lshlrev_b32_e32 v12, 16, v15
	v_and_b32_e32 v13, 0xffff0000, v15
	v_fma_f32 v10, -v2, v6, 1.0
	v_fmac_f32_e32 v6, v10, v6
	v_div_scale_f32 v10, vcc, v14, v5, v14
	v_mul_f32_e32 v25, v10, v6
	v_fma_f32 v30, -v2, v25, v10
	v_fmac_f32_e32 v25, v30, v6
	v_fma_f32 v2, -v2, v25, v10
	v_div_fmas_f32 v2, v2, v6, v25
	v_div_fixup_f32 v5, v2, v5, v14
	v_div_scale_f32 v2, s[0:1], v4, v4, v23
	v_rcp_f32_e32 v6, v2
	s_nop 0
	v_fma_f32 v10, -v2, v6, 1.0
	v_fmac_f32_e32 v6, v10, v6
	v_div_scale_f32 v10, vcc, v23, v4, v23
	v_mul_f32_e32 v14, v10, v6
	v_fma_f32 v25, -v2, v14, v10
	v_fmac_f32_e32 v14, v25, v6
	v_fma_f32 v2, -v2, v14, v10
	v_div_fmas_f32 v2, v2, v6, v14
	v_div_fixup_f32 v4, v2, v4, v23
	v_pk_fma_f32 v[8:9], v[24:25], v[32:33], v[8:9] op_sel_hi:[0,1,1]
	v_pk_mul_f32 v[4:5], v[4:5], v[8:9]
	v_and_b32_e32 v9, 0xffff0000, v3
	v_cvt_pk_bf16_f32 v2, v4, v5
	v_mul_f32_e32 v4, 0xbfb8aa3b, v12
	v_lshlrev_b32_e32 v10, 16, v3
	v_mul_f32_e32 v3, 0xbfb8aa3b, v13
	v_exp_f32_e32 v4, v4
	v_exp_f32_e32 v5, v3
	v_lshlrev_b32_e32 v8, 16, v11
	v_and_b32_e32 v11, 0xffff0000, v11
	v_pk_mul_f32 v[10:11], v[28:29], v[10:11] op_sel:[1,0] op_sel_hi:[0,1]
	v_pk_add_f32 v[4:5], v[4:5], 1.0 op_sel_hi:[1,0]
	v_pk_fma_f32 v[8:9], v[28:29], v[8:9], v[10:11]
	v_lshlrev_b32_e32 v6, 16, v7
	v_and_b32_e32 v7, 0xffff0000, v7
	v_div_scale_f32 v3, s[0:1], v5, v5, v13
	v_pk_fma_f32 v[6:7], v[24:25], v[6:7], v[8:9] op_sel_hi:[0,1,1]
	v_rcp_f32_e32 v8, v3
	s_nop 0
	v_fma_f32 v9, -v3, v8, 1.0
	v_fmac_f32_e32 v8, v9, v8
	v_div_scale_f32 v9, vcc, v13, v5, v13
	v_mul_f32_e32 v10, v9, v8
	v_fma_f32 v11, -v3, v10, v9
	v_fmac_f32_e32 v10, v11, v8
	v_fma_f32 v3, -v3, v10, v9
	v_div_fmas_f32 v3, v3, v8, v10
	v_div_fixup_f32 v5, v3, v5, v13
	v_div_scale_f32 v3, s[0:1], v4, v4, v12
	v_rcp_f32_e32 v8, v3
	s_nop 0
	v_fma_f32 v9, -v3, v8, 1.0
	v_fmac_f32_e32 v8, v9, v8
	v_div_scale_f32 v9, vcc, v12, v4, v12
	v_mul_f32_e32 v10, v9, v8
	v_fma_f32 v11, -v3, v10, v9
	v_fmac_f32_e32 v10, v11, v8
	v_fma_f32 v3, -v3, v10, v9
	v_div_fmas_f32 v3, v3, v8, v10
	v_div_fixup_f32 v4, v3, v4, v12
	v_pk_mul_f32 v[4:5], v[4:5], v[6:7]
	s_nop 0
	v_cvt_pk_bf16_f32 v3, v4, v5
	v_mad_i64_i32 v[4:5], s[0:1], v22, s37, v[26:27]
	v_lshl_add_u64 v[4:5], v[4:5], 0, v[184:185]
	v_add_co_u32_e32 v4, vcc, s74, v4
	s_nop 1
	v_addc_co_u32_e32 v5, vcc, 0, v5, vcc
	global_store_dwordx4 v[4:5], v[0:3], off offset:512
	s_nop 1
	v_add_u32_e32 v0, 0x200, v31
	v_ashrrev_i32_e32 v12, 5, v0
	v_ashrrev_i32_e32 v13, 31, v12
	v_lshl_add_u64 v[0:1], v[12:13], 4, v[18:19]
; DI float lo16(unsigned w) { return __uint_as_float(w << 16); }
; DI float hi16(unsigned w) { return __uint_as_float(w & 0xffff0000u); }
; DI float siluf_(float x) { return x / (1.f + __expf(-x)); }
; DI void dilcomb_item(const Params& p, int it) {
;     ...
;   for (int i = 0; i < 4; ++i) {
;     const int idx = it * 1024 + i * 256 + threadIdx.x;
;     const size_t tok = idx >> 5; const int c8 = idx & 31, h = c8 >> 3;
;     const float l0 = lse[((size_t)0 * T_ + tok) * 4 + h], l1 = lse[((size_t)1 * T_ + tok) * 4 + h], l2 = lse[((size_t)2 * T_ + tok) * 4 + h];
;     const float mx = fmaxf(l0, fmaxf(l1, l2));
;     float w0 = __expf(l0 - mx), w1 = __expf(l1 - mx), w2 = __expf(l2 - mx);
;     const float iw = 1.f / (w0 + w1 + w2); w0 *= iw; w1 *= iw; w2 *= iw;
;     const u32x4 a = *(const u32x4*)(od + ((size_t)0 * T_ + tok) * 256 + c8 * 8), bq = *(const u32x4*)(od + ((size_t)1 * T_ + tok) * 256 + c8 * 8), cq = *(const u32x4*)(od + ((size_t)2 * T_ + tok) * 256 + c8 * 8);
;     const u32x4 z = *(const u32x4*)(proj + tok * NP + C_BZ + c8 * 8);
;     u32x4 r;
; #pragma unroll
;     for (int e = 0; e < 4; ++e) {
;       const float v0 = (w0 * lo16(a[e]) + w1 * lo16(bq[e]) + w2 * lo16(cq[e])) * siluf_(lo16(z[e]));
;       const float v1 = (w0 * hi16(a[e]) + w1 * hi16(bq[e]) + w2 * hi16(cq[e])) * siluf_(hi16(z[e]));
;       r[e] = pk2(v0, v1);
;     }
;     *(u32x4*)(y + tok * 1024 + 256 + c8 * 8) = r;
	v_lshl_add_u64 v[4:5], v[12:13], 0, s[96:97]
	v_mov_b32_e32 v2, v153
	v_lshl_add_u64 v[0:1], v[4:5], 4, v[18:19]
	v_lshl_add_u64 v[6:7], v[12:13], 0, s[4:5]
	v_mov_b32_e32 v3, v154
	v_lshl_add_u64 v[0:1], v[6:7], 4, v[18:19]
	v_mov_b32_e32 v0, v155
	v_lshlrev_b64 v[4:5], 9, v[4:5]
	v_mad_i64_i32 v[22:23], s[0:1], v12, s33, v[20:21]
	v_lshl_add_u64 v[4:5], v[16:17], 0, v[4:5]
	v_lshl_add_u64 v[24:25], v[22:23], 0, v[184:185]
	v_max3_f32 v1, v2, v3, v0
	v_sub_f32_e32 v2, v2, v1
	v_mul_f32_e32 v2, 0x3fb8aa3b, v2
	v_exp_f32_e32 v29, v2
	v_sub_f32_e32 v2, v3, v1
	v_mul_f32_e32 v2, 0x3fb8aa3b, v2
	v_sub_f32_e32 v0, v0, v1
	v_exp_f32_e32 v28, v2
	v_mul_f32_e32 v0, 0x3fb8aa3b, v0
	v_exp_f32_e32 v0, v0
	v_add_f32_e32 v1, v29, v28
	v_add_f32_e32 v1, v0, v1
	v_div_scale_f32 v2, s[0:1], v1, v1, 1.0
	v_rcp_f32_e32 v3, v2
	s_nop 0
	v_fma_f32 v8, -v2, v3, 1.0
	v_fmac_f32_e32 v3, v8, v3
	v_div_scale_f32 v8, vcc, 1.0, v1, 1.0
	v_mul_f32_e32 v9, v8, v3
	v_fma_f32 v10, -v2, v9, v8
	v_fmac_f32_e32 v9, v10, v3
	v_fma_f32 v2, -v2, v9, v8
	v_div_fmas_f32 v2, v2, v3, v9
	v_div_fixup_f32 v30, v2, v1, 1.0
	v_mul_f32_e32 v14, v0, v30
	v_lshlrev_b64 v[0:1], 9, v[12:13]
	v_lshl_add_u64 v[0:1], v[16:17], 0, v[0:1]
	v_mov_b32_e32 v0, v108
	v_mov_b32_e32 v1, v109
	v_mov_b32_e32 v2, v110
	v_mov_b32_e32 v3, v111
	v_add_co_u32_e32 v24, vcc, s93, v24
	v_mov_b32_e32 v8, v112
	v_mov_b32_e32 v9, v113
	v_mov_b32_e32 v10, v114
	v_mov_b32_e32 v11, v115
	v_lshlrev_b64 v[4:5], 9, v[6:7]
	v_lshl_add_u64 v[4:5], v[16:17], 0, v[4:5]
	v_addc_co_u32_e32 v25, vcc, 0, v25, vcc
	v_mov_b32_e32 v4, v120
	v_mov_b32_e32 v5, v121
	v_mov_b32_e32 v6, v122
	v_mov_b32_e32 v7, v123
	v_pk_mul_f32 v[28:29], v[28:29], v[30:31] op_sel_hi:[1,0]
	v_mov_b32_e32 v24, v124
	v_mov_b32_e32 v25, v125
	v_mov_b32_e32 v26, v126
	v_mov_b32_e32 v27, v127
	v_and_b32_e32 v35, 0xffff0000, v0
	v_lshlrev_b32_e32 v36, 16, v0
	v_lshlrev_b32_e32 v34, 16, v8
	v_and_b32_e32 v37, 0xffff0000, v8
	v_pk_mul_f32 v[36:37], v[28:29], v[36:37] op_sel:[1,0] op_sel_hi:[0,1]
	v_pk_fma_f32 v[34:35], v[28:29], v[34:35], v[36:37]
	v_lshlrev_b32_e32 v38, 16, v4
	v_and_b32_e32 v39, 0xffff0000, v4
	v_lshlrev_b32_e32 v13, 16, v24
	v_and_b32_e32 v15, 0xffff0000, v24
	v_mul_f32_e32 v24, 0xbfb8aa3b, v13
	v_mul_f32_e32 v0, 0xbfb8aa3b, v15
	v_exp_f32_e32 v32, v24
	v_exp_f32_e32 v33, v0
	s_nop 0
	v_pk_add_f32 v[32:33], v[32:33], 1.0 op_sel_hi:[1,0]
	s_nop 0
	v_div_scale_f32 v0, s[0:1], v33, v33, v15
	v_rcp_f32_e32 v4, v0
	s_nop 0
	v_fma_f32 v8, -v0, v4, 1.0
	v_fmac_f32_e32 v4, v8, v4
	v_div_scale_f32 v8, vcc, v15, v33, v15
	v_mul_f32_e32 v24, v8, v4
	v_fma_f32 v30, -v0, v24, v8
	v_fmac_f32_e32 v24, v30, v4
	v_fma_f32 v0, -v0, v24, v8
	v_div_fmas_f32 v0, v0, v4, v24
	v_div_fixup_f32 v33, v0, v33, v15
	v_div_scale_f32 v0, s[0:1], v32, v32, v13
	v_rcp_f32_e32 v4, v0
	s_nop 0
	v_fma_f32 v8, -v0, v4, 1.0
	v_fmac_f32_e32 v4, v8, v4
	v_div_scale_f32 v8, vcc, v13, v32, v13
	v_mul_f32_e32 v15, v8, v4
	v_fma_f32 v24, -v0, v15, v8
	v_fmac_f32_e32 v15, v24, v4
	v_fma_f32 v0, -v0, v15, v8
	v_div_fmas_f32 v0, v0, v4, v15
	v_div_fixup_f32 v32, v0, v32, v13
	v_pk_fma_f32 v[34:35], v[14:15], v[38:39], v[34:35] op_sel_hi:[0,1,1]
	v_lshlrev_b32_e32 v13, 16, v25
	v_and_b32_e32 v15, 0xffff0000, v25
	v_pk_mul_f32 v[32:33], v[32:33], v[34:35]
	v_mul_f32_e32 v4, 0xbfb8aa3b, v13
	v_and_b32_e32 v25, 0xffff0000, v1
	v_lshlrev_b32_e32 v8, 16, v1
	v_mul_f32_e32 v1, 0xbfb8aa3b, v15
	v_cvt_pk_bf16_f32 v0, v32, v33
	v_exp_f32_e32 v4, v4
	v_lshlrev_b32_e32 v32, 16, v5
	v_and_b32_e32 v33, 0xffff0000, v5
	v_exp_f32_e32 v5, v1
	v_lshlrev_b32_e32 v24, 16, v9
	v_and_b32_e32 v9, 0xffff0000, v9
	v_pk_mul_f32 v[8:9], v[28:29], v[8:9] op_sel:[1,0] op_sel_hi:[0,1]
	v_pk_add_f32 v[4:5], v[4:5], 1.0 op_sel_hi:[1,0]
	v_pk_fma_f32 v[8:9], v[28:29], v[24:25], v[8:9]
	v_div_scale_f32 v1, s[0:1], v5, v5, v15
	v_rcp_f32_e32 v30, v1
	v_lshlrev_b32_e32 v24, 16, v2
	v_and_b32_e32 v25, 0xffff0000, v10
	v_pk_mul_f32 v[24:25], v[28:29], v[24:25] op_sel:[1,0] op_sel_hi:[0,1]
	v_fma_f32 v34, -v1, v30, 1.0
	v_fmac_f32_e32 v30, v34, v30
	v_div_scale_f32 v34, vcc, v15, v5, v15
	v_mul_f32_e32 v35, v34, v30
	v_fma_f32 v36, -v1, v35, v34
	v_fmac_f32_e32 v35, v36, v30
	v_fma_f32 v1, -v1, v35, v34
	v_div_fmas_f32 v1, v1, v30, v35
	v_div_fixup_f32 v5, v1, v5, v15
	v_div_scale_f32 v1, s[0:1], v4, v4, v13
	v_rcp_f32_e32 v15, v1
	s_nop 0
	v_fma_f32 v30, -v1, v15, 1.0
	v_fmac_f32_e32 v15, v30, v15
	v_div_scale_f32 v30, vcc, v13, v4, v13
	v_mul_f32_e32 v34, v30, v15
	v_fma_f32 v35, -v1, v34, v30
	v_fmac_f32_e32 v34, v35, v15
	v_fma_f32 v1, -v1, v34, v30
	v_div_fmas_f32 v1, v1, v15, v34
	v_div_fixup_f32 v4, v1, v4, v13
	v_pk_fma_f32 v[8:9], v[14:15], v[32:33], v[8:9] op_sel_hi:[0,1,1]
	v_pk_mul_f32 v[4:5], v[4:5], v[8:9]
	v_lshlrev_b32_e32 v13, 16, v26
	v_and_b32_e32 v15, 0xffff0000, v26
	v_cvt_pk_bf16_f32 v1, v4, v5
	v_mul_f32_e32 v4, 0xbfb8aa3b, v13
	v_and_b32_e32 v9, 0xffff0000, v2
	v_mul_f32_e32 v2, 0xbfb8aa3b, v15
	v_exp_f32_e32 v4, v4
	v_exp_f32_e32 v5, v2
	v_lshlrev_b32_e32 v32, 16, v6
	v_and_b32_e32 v33, 0xffff0000, v6
	v_lshlrev_b32_e32 v8, 16, v10
	v_pk_add_f32 v[4:5], v[4:5], 1.0 op_sel_hi:[1,0]
	v_pk_fma_f32 v[8:9], v[28:29], v[8:9], v[24:25]
	v_div_scale_f32 v2, s[0:1], v5, v5, v15
	v_rcp_f32_e32 v6, v2
	s_nop 0
	v_fma_f32 v10, -v2, v6, 1.0
	v_fmac_f32_e32 v6, v10, v6
	v_div_scale_f32 v10, vcc, v15, v5, v15
	v_mul_f32_e32 v26, v10, v6
	v_fma_f32 v30, -v2, v26, v10
	v_fmac_f32_e32 v26, v30, v6
	v_fma_f32 v2, -v2, v26, v10
	v_div_fmas_f32 v2, v2, v6, v26
	v_div_fixup_f32 v5, v2, v5, v15
	v_div_scale_f32 v2, s[0:1], v4, v4, v13
	v_rcp_f32_e32 v6, v2
	s_nop 0
	v_fma_f32 v10, -v2, v6, 1.0
	v_fmac_f32_e32 v6, v10, v6
; DI float lo16(unsigned w) { return __uint_as_float(w << 16); }
; DI float hi16(unsigned w) { return __uint_as_float(w & 0xffff0000u); }
; DI float siluf_(float x) { return x / (1.f + __expf(-x)); }
; DI void dilcomb_item(const Params& p, int it) {
;     ...
;   for (int i = 0; i < 4; ++i) {
;     const int idx = it * 1024 + i * 256 + threadIdx.x;
;     const size_t tok = idx >> 5; const int c8 = idx & 31, h = c8 >> 3;
;     const float l0 = lse[((size_t)0 * T_ + tok) * 4 + h], l1 = lse[((size_t)1 * T_ + tok) * 4 + h], l2 = lse[((size_t)2 * T_ + tok) * 4 + h];
;     const float mx = fmaxf(l0, fmaxf(l1, l2));
;     float w0 = __expf(l0 - mx), w1 = __expf(l1 - mx), w2 = __expf(l2 - mx);
;     const float iw = 1.f / (w0 + w1 + w2); w0 *= iw; w1 *= iw; w2 *= iw;
;     const u32x4 a = *(const u32x4*)(od + ((size_t)0 * T_ + tok) * 256 + c8 * 8), bq = *(const u32x4*)(od + ((size_t)1 * T_ + tok) * 256 + c8 * 8), cq = *(const u32x4*)(od + ((size_t)2 * T_ + tok) * 256 + c8 * 8);
;     const u32x4 z = *(const u32x4*)(proj + tok * NP + C_BZ + c8 * 8);
;     u32x4 r;
; #pragma unroll
;     for (int e = 0; e < 4; ++e) {
;       const float v0 = (w0 * lo16(a[e]) + w1 * lo16(bq[e]) + w2 * lo16(cq[e])) * siluf_(lo16(z[e]));
;       const float v1 = (w0 * hi16(a[e]) + w1 * hi16(bq[e]) + w2 * hi16(cq[e])) * siluf_(hi16(z[e]));
;       r[e] = pk2(v0, v1);
;     }
;     *(u32x4*)(y + tok * 1024 + 256 + c8 * 8) = r;
	v_div_scale_f32 v10, vcc, v13, v4, v13
	v_mul_f32_e32 v15, v10, v6
	v_fma_f32 v26, -v2, v15, v10
	v_fmac_f32_e32 v15, v26, v6
	v_fma_f32 v2, -v2, v15, v10
	v_div_fmas_f32 v2, v2, v6, v15
	v_div_fixup_f32 v4, v2, v4, v13
	v_pk_fma_f32 v[8:9], v[14:15], v[32:33], v[8:9] op_sel_hi:[0,1,1]
	v_pk_mul_f32 v[4:5], v[4:5], v[8:9]
	v_lshlrev_b32_e32 v13, 16, v27
	v_and_b32_e32 v15, 0xffff0000, v27
	v_cvt_pk_bf16_f32 v2, v4, v5
	v_mul_f32_e32 v4, 0xbfb8aa3b, v13
	v_and_b32_e32 v9, 0xffff0000, v3
	v_lshlrev_b32_e32 v10, 16, v3
	v_mul_f32_e32 v3, 0xbfb8aa3b, v15
	v_exp_f32_e32 v4, v4
	v_exp_f32_e32 v5, v3
	v_lshlrev_b32_e32 v8, 16, v11
	v_and_b32_e32 v11, 0xffff0000, v11
	v_pk_mul_f32 v[10:11], v[28:29], v[10:11] op_sel:[1,0] op_sel_hi:[0,1]
	v_pk_add_f32 v[4:5], v[4:5], 1.0 op_sel_hi:[1,0]
	v_pk_fma_f32 v[8:9], v[28:29], v[8:9], v[10:11]
	v_lshlrev_b32_e32 v6, 16, v7
	v_and_b32_e32 v7, 0xffff0000, v7
	v_div_scale_f32 v3, s[0:1], v5, v5, v15
	v_pk_fma_f32 v[6:7], v[14:15], v[6:7], v[8:9] op_sel_hi:[0,1,1]
	v_rcp_f32_e32 v8, v3
	s_nop 0
	v_fma_f32 v9, -v3, v8, 1.0
	v_fmac_f32_e32 v8, v9, v8
	v_div_scale_f32 v9, vcc, v15, v5, v15
	v_mul_f32_e32 v10, v9, v8
	v_fma_f32 v11, -v3, v10, v9
	v_fmac_f32_e32 v10, v11, v8
	v_fma_f32 v3, -v3, v10, v9
	v_div_fmas_f32 v3, v3, v8, v10
	v_div_fixup_f32 v5, v3, v5, v15
	v_div_scale_f32 v3, s[0:1], v4, v4, v13
	v_rcp_f32_e32 v8, v3
	s_nop 0
	v_fma_f32 v9, -v3, v8, 1.0
	v_fmac_f32_e32 v8, v9, v8
	v_div_scale_f32 v9, vcc, v13, v4, v13
	v_mul_f32_e32 v10, v9, v8
	v_fma_f32 v11, -v3, v10, v9
	v_fmac_f32_e32 v10, v11, v8
	v_fma_f32 v3, -v3, v10, v9
	v_div_fmas_f32 v3, v3, v8, v10
	v_div_fixup_f32 v4, v3, v4, v13
	v_pk_mul_f32 v[4:5], v[4:5], v[6:7]
	s_nop 0
	v_cvt_pk_bf16_f32 v3, v4, v5
	v_mad_i64_i32 v[4:5], s[0:1], v12, s37, v[22:23]
	v_lshl_add_u64 v[4:5], v[4:5], 0, v[184:185]
	v_add_co_u32_e32 v4, vcc, s74, v4
	s_nop 1
	v_addc_co_u32_e32 v5, vcc, 0, v5, vcc
	global_store_dwordx4 v[4:5], v[0:3], off offset:512
	s_nop 1
	v_add_u32_e32 v0, 0x300, v31
	v_ashrrev_i32_e32 v22, 5, v0
	v_ashrrev_i32_e32 v23, 31, v22
	v_lshl_add_u64 v[0:1], v[22:23], 4, v[18:19]
	v_lshl_add_u64 v[4:5], v[22:23], 0, s[96:97]
	v_mov_b32_e32 v2, v156
	v_lshl_add_u64 v[0:1], v[4:5], 4, v[18:19]
	v_lshl_add_u64 v[6:7], v[22:23], 0, s[4:5]
	v_mov_b32_e32 v3, v157
	v_lshl_add_u64 v[0:1], v[6:7], 4, v[18:19]
	v_mov_b32_e32 v0, v158
	v_lshlrev_b64 v[4:5], 9, v[4:5]
	v_lshl_add_u64 v[4:5], v[16:17], 0, v[4:5]
	v_max3_f32 v1, v2, v3, v0
	v_sub_f32_e32 v2, v2, v1
	v_mul_f32_e32 v2, 0x3fb8aa3b, v2
	v_exp_f32_e32 v25, v2
	v_sub_f32_e32 v2, v3, v1
	v_mul_f32_e32 v2, 0x3fb8aa3b, v2
	v_sub_f32_e32 v0, v0, v1
	v_exp_f32_e32 v24, v2
	v_mul_f32_e32 v0, 0x3fb8aa3b, v0
	v_exp_f32_e32 v0, v0
	v_add_f32_e32 v1, v25, v24
	v_add_f32_e32 v1, v0, v1
	v_div_scale_f32 v2, s[0:1], v1, v1, 1.0
	v_rcp_f32_e32 v3, v2
	s_nop 0
	v_fma_f32 v8, -v2, v3, 1.0
	v_fmac_f32_e32 v3, v8, v3
	v_div_scale_f32 v8, vcc, 1.0, v1, 1.0
	v_mul_f32_e32 v9, v8, v3
	v_fma_f32 v10, -v2, v9, v8
	v_fmac_f32_e32 v9, v10, v3
	v_fma_f32 v2, -v2, v9, v8
	v_div_fmas_f32 v2, v2, v3, v9
	v_div_fixup_f32 v26, v2, v1, 1.0
	v_mul_f32_e32 v18, v0, v26
	v_lshlrev_b64 v[0:1], 9, v[22:23]
	v_lshl_add_u64 v[0:1], v[16:17], 0, v[0:1]
	v_mov_b32_e32 v0, v128
	v_mov_b32_e32 v1, v129
	v_mov_b32_e32 v2, v130
	v_mov_b32_e32 v3, v131
	s_nop 0
	v_mov_b32_e32 v8, v132
	v_mov_b32_e32 v9, v133
	v_mov_b32_e32 v10, v134
	v_mov_b32_e32 v11, v135
	v_lshlrev_b64 v[4:5], 9, v[6:7]
	v_lshl_add_u64 v[4:5], v[16:17], 0, v[4:5]
	v_mad_i64_i32 v[16:17], s[0:1], v22, s33, v[20:21]
	v_lshl_add_u64 v[12:13], v[16:17], 0, v[184:185]
	v_add_co_u32_e32 v12, vcc, s93, v12
	v_mov_b32_e32 v4, v136
	v_mov_b32_e32 v5, v137
	v_mov_b32_e32 v6, v138
	v_mov_b32_e32 v7, v139
	s_nop 0
	v_addc_co_u32_e32 v13, vcc, 0, v13, vcc
	v_mov_b32_e32 v12, v140
	v_mov_b32_e32 v13, v141
	v_mov_b32_e32 v14, v142
	v_mov_b32_e32 v15, v143
	v_pk_mul_f32 v[20:21], v[24:25], v[26:27] op_sel_hi:[1,0]
	v_and_b32_e32 v27, 0xffff0000, v0
	v_lshlrev_b32_e32 v28, 16, v0
	v_lshlrev_b32_e32 v26, 16, v8
	v_and_b32_e32 v29, 0xffff0000, v8
	v_pk_mul_f32 v[28:29], v[20:21], v[28:29] op_sel:[1,0] op_sel_hi:[0,1]
	v_pk_fma_f32 v[26:27], v[20:21], v[26:27], v[28:29]
	v_lshlrev_b32_e32 v30, 16, v4
	v_and_b32_e32 v31, 0xffff0000, v4
	v_lshlrev_b32_e32 v19, 16, v12
	v_and_b32_e32 v12, 0xffff0000, v12
	v_mul_f32_e32 v23, 0xbfb8aa3b, v19
	v_mul_f32_e32 v0, 0xbfb8aa3b, v12
	v_exp_f32_e32 v24, v23
	v_exp_f32_e32 v25, v0
	v_pk_fma_f32 v[26:27], v[18:19], v[30:31], v[26:27] op_sel_hi:[0,1,1]
	v_pk_add_f32 v[24:25], v[24:25], 1.0 op_sel_hi:[1,0]
	s_nop 0
	v_div_scale_f32 v0, s[0:1], v25, v25, v12
	v_rcp_f32_e32 v4, v0
	s_nop 0
	v_fma_f32 v8, -v0, v4, 1.0
	v_fmac_f32_e32 v4, v8, v4
	v_div_scale_f32 v8, vcc, v12, v25, v12
	v_mul_f32_e32 v23, v8, v4
	v_fma_f32 v32, -v0, v23, v8
	v_fmac_f32_e32 v23, v32, v4
	v_fma_f32 v0, -v0, v23, v8
	v_div_fmas_f32 v0, v0, v4, v23
; DI float lo16(unsigned w) { return __uint_as_float(w << 16); }
; DI float hi16(unsigned w) { return __uint_as_float(w & 0xffff0000u); }
; DI float siluf_(float x) { return x / (1.f + __expf(-x)); }
; DI void dilcomb_item(const Params& p, int it) {
;     ...
;   for (int i = 0; i < 4; ++i) {
;     const int idx = it * 1024 + i * 256 + threadIdx.x;
;     const size_t tok = idx >> 5; const int c8 = idx & 31, h = c8 >> 3;
;     const float l0 = lse[((size_t)0 * T_ + tok) * 4 + h], l1 = lse[((size_t)1 * T_ + tok) * 4 + h], l2 = lse[((size_t)2 * T_ + tok) * 4 + h];
;     const float mx = fmaxf(l0, fmaxf(l1, l2));
;     float w0 = __expf(l0 - mx), w1 = __expf(l1 - mx), w2 = __expf(l2 - mx);
;     const float iw = 1.f / (w0 + w1 + w2); w0 *= iw; w1 *= iw; w2 *= iw;
;     const u32x4 a = *(const u32x4*)(od + ((size_t)0 * T_ + tok) * 256 + c8 * 8), bq = *(const u32x4*)(od + ((size_t)1 * T_ + tok) * 256 + c8 * 8), cq = *(const u32x4*)(od + ((size_t)2 * T_ + tok) * 256 + c8 * 8);
;     const u32x4 z = *(const u32x4*)(proj + tok * NP + C_BZ + c8 * 8);
;     u32x4 r;
; #pragma unroll
;     for (int e = 0; e < 4; ++e) {
;       const float v0 = (w0 * lo16(a[e]) + w1 * lo16(bq[e]) + w2 * lo16(cq[e])) * siluf_(lo16(z[e]));
;       const float v1 = (w0 * hi16(a[e]) + w1 * hi16(bq[e]) + w2 * hi16(cq[e])) * siluf_(hi16(z[e]));
;       r[e] = pk2(v0, v1);
;     }
;     *(u32x4*)(y + tok * 1024 + 256 + c8 * 8) = r;
; __global__ void __launch_bounds__(256, 2) hybrid_megakernel(Params p) {
;     ...
;       for (int k = 0; k < mine; ++k) { const int slot = start + k; sgu_item(p, l, slot * 8 + x, lds); pool_item(p, l, slot * 8 + x, lds); dilcomb_item(p, x * 64 + slot); }
	v_div_fixup_f32 v25, v0, v25, v12
	v_div_scale_f32 v0, s[0:1], v24, v24, v19
	v_rcp_f32_e32 v4, v0
	s_nop 0
	v_fma_f32 v8, -v0, v4, 1.0
	v_fmac_f32_e32 v4, v8, v4
	v_div_scale_f32 v8, vcc, v19, v24, v19
	v_mul_f32_e32 v12, v8, v4
	v_fma_f32 v23, -v0, v12, v8
	v_fmac_f32_e32 v12, v23, v4
	v_fma_f32 v0, -v0, v12, v8
	v_div_fmas_f32 v0, v0, v4, v12
	v_div_fixup_f32 v24, v0, v24, v19
	v_lshlrev_b32_e32 v19, 16, v13
	v_and_b32_e32 v23, 0xffff0000, v13
	v_pk_mul_f32 v[24:25], v[24:25], v[26:27]
	v_mul_f32_e32 v4, 0xbfb8aa3b, v19
	v_and_b32_e32 v13, 0xffff0000, v1
	v_lshlrev_b32_e32 v8, 16, v1
	v_mul_f32_e32 v1, 0xbfb8aa3b, v23
	v_cvt_pk_bf16_f32 v0, v24, v25
	v_exp_f32_e32 v4, v4
	v_lshlrev_b32_e32 v24, 16, v5
	v_and_b32_e32 v25, 0xffff0000, v5
	v_exp_f32_e32 v5, v1
	v_lshlrev_b32_e32 v12, 16, v9
	v_and_b32_e32 v9, 0xffff0000, v9
	v_pk_mul_f32 v[8:9], v[20:21], v[8:9] op_sel:[1,0] op_sel_hi:[0,1]
	v_pk_add_f32 v[4:5], v[4:5], 1.0 op_sel_hi:[1,0]
	v_pk_fma_f32 v[8:9], v[20:21], v[12:13], v[8:9]
	v_div_scale_f32 v1, s[0:1], v5, v5, v23
	v_rcp_f32_e32 v26, v1
	v_pk_fma_f32 v[8:9], v[18:19], v[24:25], v[8:9] op_sel_hi:[0,1,1]
	v_lshlrev_b32_e32 v12, 16, v2
	v_lshlrev_b32_e32 v24, 16, v6
	v_fma_f32 v27, -v1, v26, 1.0
	v_fmac_f32_e32 v26, v27, v26
	v_div_scale_f32 v27, vcc, v23, v5, v23
	v_mul_f32_e32 v28, v27, v26
	v_fma_f32 v29, -v1, v28, v27
	v_fmac_f32_e32 v28, v29, v26
	v_fma_f32 v1, -v1, v28, v27
	v_div_fmas_f32 v1, v1, v26, v28
	v_div_fixup_f32 v5, v1, v5, v23
	v_div_scale_f32 v1, s[0:1], v4, v4, v19
	v_rcp_f32_e32 v23, v1
	v_and_b32_e32 v25, 0xffff0000, v6
	v_and_b32_e32 v13, 0xffff0000, v10
	v_pk_mul_f32 v[12:13], v[20:21], v[12:13] op_sel:[1,0] op_sel_hi:[0,1]
	v_fma_f32 v26, -v1, v23, 1.0
	v_fmac_f32_e32 v23, v26, v23
	v_div_scale_f32 v26, vcc, v19, v4, v19
	v_mul_f32_e32 v27, v26, v23
	v_fma_f32 v28, -v1, v27, v26
	v_fmac_f32_e32 v27, v28, v23
	v_fma_f32 v1, -v1, v27, v26
	v_div_fmas_f32 v1, v1, v23, v27
	v_div_fixup_f32 v4, v1, v4, v19
	v_pk_mul_f32 v[4:5], v[4:5], v[8:9]
	v_lshlrev_b32_e32 v19, 16, v14
	v_and_b32_e32 v14, 0xffff0000, v14
	v_cvt_pk_bf16_f32 v1, v4, v5
	v_mul_f32_e32 v4, 0xbfb8aa3b, v19
	v_and_b32_e32 v9, 0xffff0000, v2
	v_mul_f32_e32 v2, 0xbfb8aa3b, v14
	v_exp_f32_e32 v4, v4
	v_exp_f32_e32 v5, v2
	v_lshlrev_b32_e32 v8, 16, v10
	v_pk_fma_f32 v[8:9], v[20:21], v[8:9], v[12:13]
	v_lshlrev_b32_e32 v12, 16, v15
	v_pk_add_f32 v[4:5], v[4:5], 1.0 op_sel_hi:[1,0]
	v_pk_fma_f32 v[8:9], v[18:19], v[24:25], v[8:9] op_sel_hi:[0,1,1]
	v_div_scale_f32 v2, s[0:1], v5, v5, v14
	v_rcp_f32_e32 v6, v2
	v_and_b32_e32 v13, 0xffff0000, v15
	v_fma_f32 v10, -v2, v6, 1.0
	v_fmac_f32_e32 v6, v10, v6
	v_div_scale_f32 v10, vcc, v14, v5, v14
	v_mul_f32_e32 v23, v10, v6
	v_fma_f32 v26, -v2, v23, v10
	v_fmac_f32_e32 v23, v26, v6
	v_fma_f32 v2, -v2, v23, v10
	v_div_fmas_f32 v2, v2, v6, v23
	v_div_fixup_f32 v5, v2, v5, v14
	v_div_scale_f32 v2, s[0:1], v4, v4, v19
	v_rcp_f32_e32 v6, v2
	s_nop 0
	v_fma_f32 v10, -v2, v6, 1.0
	v_fmac_f32_e32 v6, v10, v6
	v_div_scale_f32 v10, vcc, v19, v4, v19
	v_mul_f32_e32 v14, v10, v6
	v_fma_f32 v23, -v2, v14, v10
	v_fmac_f32_e32 v14, v23, v6
	v_fma_f32 v2, -v2, v14, v10
	v_div_fmas_f32 v2, v2, v6, v14
	v_div_fixup_f32 v4, v2, v4, v19
	v_pk_mul_f32 v[4:5], v[4:5], v[8:9]
	v_and_b32_e32 v9, 0xffff0000, v3
	v_cvt_pk_bf16_f32 v2, v4, v5
	v_mul_f32_e32 v4, 0xbfb8aa3b, v12
	v_lshlrev_b32_e32 v10, 16, v3
	v_mul_f32_e32 v3, 0xbfb8aa3b, v13
	v_exp_f32_e32 v4, v4
	v_exp_f32_e32 v5, v3
	v_lshlrev_b32_e32 v8, 16, v11
	v_and_b32_e32 v11, 0xffff0000, v11
	v_pk_mul_f32 v[10:11], v[20:21], v[10:11] op_sel:[1,0] op_sel_hi:[0,1]
	v_pk_add_f32 v[4:5], v[4:5], 1.0 op_sel_hi:[1,0]
	v_pk_fma_f32 v[8:9], v[20:21], v[8:9], v[10:11]
	v_lshlrev_b32_e32 v6, 16, v7
	v_and_b32_e32 v7, 0xffff0000, v7
	v_div_scale_f32 v3, s[0:1], v5, v5, v13
	v_pk_fma_f32 v[6:7], v[18:19], v[6:7], v[8:9] op_sel_hi:[0,1,1]
	v_rcp_f32_e32 v8, v3
	s_nop 0
	v_fma_f32 v9, -v3, v8, 1.0
	v_fmac_f32_e32 v8, v9, v8
	v_div_scale_f32 v9, vcc, v13, v5, v13
	v_mul_f32_e32 v10, v9, v8
	v_fma_f32 v11, -v3, v10, v9
	v_fmac_f32_e32 v10, v11, v8
	v_fma_f32 v3, -v3, v10, v9
	v_div_fmas_f32 v3, v3, v8, v10
	v_div_fixup_f32 v5, v3, v5, v13
	v_div_scale_f32 v3, s[0:1], v4, v4, v12
	v_rcp_f32_e32 v8, v3
	s_nop 0
	v_fma_f32 v9, -v3, v8, 1.0
	v_fmac_f32_e32 v8, v9, v8
	v_div_scale_f32 v9, vcc, v12, v4, v12
	v_mul_f32_e32 v10, v9, v8
	v_fma_f32 v11, -v3, v10, v9
	v_fmac_f32_e32 v10, v11, v8
	v_fma_f32 v3, -v3, v10, v9
	v_div_fmas_f32 v3, v3, v8, v10
	v_div_fixup_f32 v4, v3, v4, v12
	v_pk_mul_f32 v[4:5], v[4:5], v[6:7]
	s_nop 0
	v_cvt_pk_bf16_f32 v3, v4, v5
	v_mad_i64_i32 v[4:5], s[0:1], v22, s37, v[16:17]
	v_lshl_add_u64 v[4:5], v[4:5], 0, v[184:185]
	v_add_co_u32_e32 v4, vcc, 0x2a40000, v4
	s_nop 1
	v_addc_co_u32_e32 v5, vcc, 0, v5, vcc
	v_cmp_eq_u32_e32 vcc, s6, v116
	global_store_dwordx4 v[4:5], v[0:3], off offset:512
	s_cbranch_vccz .LBB0_411
	s_branch .LBB0_345

; __global__ void __launch_bounds__(256, 2) hybrid_megakernel(Params p) {
;   __shared__ __attribute__((aligned(16))) char lds[73728];
	.amdhsa_kernel _Z17hybrid_megakernel6Params
		.amdhsa_group_segment_fixed_size 73760
		.amdhsa_private_segment_fixed_size 0
		.amdhsa_kernarg_size 384
		.amdhsa_user_sgpr_count 2
		.amdhsa_user_sgpr_dispatch_ptr 0
		.amdhsa_user_sgpr_queue_ptr 0
		.amdhsa_user_sgpr_kernarg_segment_ptr 1
		.amdhsa_user_sgpr_dispatch_id 0
		.amdhsa_user_sgpr_kernarg_preload_length 0
		.amdhsa_user_sgpr_kernarg_preload_offset 0
		.amdhsa_user_sgpr_private_segment_size 0
		.amdhsa_uses_dynamic_stack 0
		.amdhsa_enable_private_segment 0
		.amdhsa_system_sgpr_workgroup_id_x 1
		.amdhsa_system_sgpr_workgroup_id_y 0
		.amdhsa_system_sgpr_workgroup_id_z 0
		.amdhsa_system_sgpr_workgroup_info 0
		.amdhsa_system_vgpr_workitem_id 2
		.amdhsa_next_free_vgpr 240
		.amdhsa_next_free_sgpr 98
		.amdhsa_accum_offset 240
		.amdhsa_reserve_vcc 1
		.amdhsa_float_round_mode_32 0
		.amdhsa_float_round_mode_16_64 0
		.amdhsa_float_denorm_mode_32 3
		.amdhsa_float_denorm_mode_16_64 3
		.amdhsa_dx10_clamp 1
		.amdhsa_ieee_mode 1
		.amdhsa_fp16_overflow 0
		.amdhsa_tg_split 0
		.amdhsa_exception_fp_ieee_invalid_op 0
		.amdhsa_exception_fp_denorm_src 0
		.amdhsa_exception_fp_ieee_div_zero 0
		.amdhsa_exception_fp_ieee_overflow 0
		.amdhsa_exception_fp_ieee_underflow 0
		.amdhsa_exception_fp_ieee_inexact 0
		.amdhsa_exception_int_div_zero 0
	.end_amdhsa_kernel

; __global__ void __launch_bounds__(256, 2) hybrid_megakernel(Params p) {
;   __shared__ __attribute__((aligned(16))) char lds[73728];
amdhsa.kernels:
  - .agpr_count:     0
    .args:
      - .offset:         0
        .size:           128
        .value_kind:     by_value
      - .offset:         128
        .size:           4
        .value_kind:     hidden_block_count_x
      - .offset:         132
        .size:           4
        .value_kind:     hidden_block_count_y
      - .offset:         136
        .size:           4
        .value_kind:     hidden_block_count_z
      - .offset:         140
        .size:           2
        .value_kind:     hidden_group_size_x
      - .offset:         142
        .size:           2
        .value_kind:     hidden_group_size_y
      - .offset:         144
        .size:           2
        .value_kind:     hidden_group_size_z
      - .offset:         146
        .size:           2
        .value_kind:     hidden_remainder_x
      - .offset:         148
        .size:           2
        .value_kind:     hidden_remainder_y
      - .offset:         150
        .size:           2
        .value_kind:     hidden_remainder_z
      - .offset:         168
        .size:           8
        .value_kind:     hidden_global_offset_x
      - .offset:         176
        .size:           8
        .value_kind:     hidden_global_offset_y
      - .offset:         184
        .size:           8
        .value_kind:     hidden_global_offset_z
      - .offset:         192
        .size:           2
        .value_kind:     hidden_grid_dims
      - .offset:         216
        .size:           8
        .value_kind:     hidden_multigrid_sync_arg
    .group_segment_fixed_size: 73760
    .kernarg_segment_align: 8
    .kernarg_segment_size: 384
    .language:       OpenCL C
    .language_version:
      - 2
      - 0
    .max_flat_workgroup_size: 256
    .name:           _Z17hybrid_megakernel6Params
    .private_segment_fixed_size: 0
    .sgpr_count:     104
    .sgpr_spill_count: 167
    .symbol:         _Z17hybrid_megakernel6Params.kd
    .uniform_work_group_size: 1
    .uses_dynamic_stack: false
    .vgpr_count:     240
    .vgpr_spill_count: 0
    .wavefront_size: 64
